# norm phases: context-row fold handled by a streamed handler (7 slice buffers in flight, fixed slice order) instead of 3 serialized 16-load batches
# baseline (speedup 1.0000x reference)
; #define NP_LOAD(dst_, r_) do { const float* s_ = NP_SRC(r_); _Pragma("unroll") for (int j = 0; j < 4; ++j) dst_[j] = *(const f32x4*)(s_ + 4 * lane + 256 * j); } while (0)
; DI void norm_phase(const Ctx& a, int layer, int sub, bool first, const float* P, int nsl, int nrows) {
;     ...
;     for (int j = 0; j < 4; ++j) { gg[j] = *(const f32x4*)(g + 4 * lane + 256 * j); n1[j] = (f32x4){0.f, 0.f, 0.f, 0.f}; n2[j] = n1[j]; sc[j] = n1[j]; sh[j] = n1[j]; }
;     NP_LOAD(n1, rbeg);
;     if (rbeg + NGW < rend) NP_LOAD(n2, rbeg + NGW);
;     int mr_cur = -1;
;     for (int row = rbeg; row < rend; row += NGW) {
; #pragma unroll
;         for (int j = 0; j < 4; ++j) { v[j] = n1[j]; n1[j] = n2[j]; }
;         if (row + 2 * NGW < rend) NP_LOAD(n2, row + 2 * NGW);
;         const int mr = row < ML ? (row >> 12) : 4;
;         if (mr != mr_cur) { mr_cur = mr;
; #pragma unroll
;             for (int j = 0; j < 4; ++j) { sh[j] = *(const f32x4*)(modl + (size_t)mr * MODW + 4 * lane + 256 * j); sc[j] = *(const f32x4*)(modl + (size_t)mr * MODW + 1024 + 4 * lane + 256 * j) + 1.f; } }
;         const bool fold = !first && row >= ML;
;         float ss = 0.f;
;         if (fold) {
;             for (int sl0 = 0; sl0 < nsl; sl0 += 4) {
;                 f32x4 t[4][4]; float wq[4];
; #pragma unroll
;                 for (int u = 0; u < 4; ++u) { const int sl = sl0 + u < nsl ? sl0 + u : nsl - 1; wq[u] = sl0 + u < nsl ? 1.f : 0.f;
; #pragma unroll
;                     for (int j = 0; j < 4; ++j) t[u][j] = *(const f32x4*)(P + ((size_t)sl * MC + (row - ML)) * D + 4 * lane + 256 * j); }
; #pragma unroll
;                 for (int u = 0; u < 4; ++u)
; #pragma unroll
;                     for (int j = 0; j < 4; ++j) v[j] = v[j] + t[u][j] * wq[u];
;             }
;         }
; #pragma unroll
;         for (int j = 0; j < 4; ++j) ss += (v[j][0] * v[j][0] + v[j][1] * v[j][1]) + (v[j][2] * v[j][2] + v[j][3] * v[j][3]);
;         const float rstd = 1.f / sqrtf(wave_sum(ss, lane) * (1.f / 1024.f) + 1e-6f);
.LBB0_501:
	s_or_b64 exec, exec, s[42:43]
	v_readlane_b32 s6, v254, 59
	v_readlane_b32 s7, v254, 60
	s_and_b64 s[42:43], s[6:7], exec
	v_readlane_b32 s6, v254, 55
	v_readlane_b32 s7, v254, 56
	s_cselect_b32 s20, 1, 4
	s_and_b64 s[42:43], s[6:7], exec
	s_cselect_b32 s20, 8, s20
	s_and_b64 s[42:43], s[40:41], exec
	s_mov_b32 s1, 0x1103a200
	s_cselect_b32 s21, s1, 0x1983a200
	s_add_u32 s42, s38, s21
	s_addc_u32 s43, s39, 0
	s_and_b64 s[40:41], s[40:41], exec
	v_readlane_b32 s1, v255, 10
	s_cselect_b32 s48, s20, 11
	s_mul_hi_i32 s20, s75, 0x2d000
	s_add_u32 s21, s38, s1
	s_addc_u32 s20, s39, s20
	s_mulk_i32 s46, 0x3000
	v_mov_b32_e32 v62, v147
	v_mov_b32_e32 v63, v147
	s_add_u32 s38, s21, s46
	v_lshlrev_b32_e32 v44, 1, v46
	v_mov_b32_e32 v45, v147
	v_mov_b32_e32 v60, v147
	v_mov_b32_e32 v61, v147
	v_mov_b64_e32 v[70:71], v[62:63]
	v_mov_b64_e32 v[74:75], v[62:63]
	v_mov_b64_e32 v[78:79], v[62:63]
	v_mov_b64_e32 v[86:87], v[62:63]
	v_mov_b64_e32 v[82:83], v[62:63]
	v_mov_b64_e32 v[90:91], v[62:63]
	v_mov_b64_e32 v[94:95], v[62:63]
	s_addc_u32 s39, s20, 0
	s_add_i32 s49, s48, -1
	v_lshl_add_u64 v[98:99], s[42:43], 0, v[146:147]
	v_xor_b32_e32 v108, 64, v46
	v_xor_b32_e32 v109, 0x80, v46
	v_lshl_add_u64 v[100:101], s[4:5], 0, v[44:45]
	v_mov_b32_e32 v110, -1
	s_mov_b64 s[44:45], 0
	s_xor_b64 s[46:47], s[30:31], -1
	v_mov_b64_e32 v[68:69], v[60:61]
	v_mov_b64_e32 v[72:73], v[60:61]
	v_mov_b64_e32 v[76:77], v[60:61]
	v_mov_b64_e32 v[84:85], v[60:61]
	v_mov_b64_e32 v[80:81], v[60:61]
	v_mov_b64_e32 v[88:89], v[60:61]
	v_mov_b64_e32 v[92:93], v[60:61]
	s_and_b64 vcc, exec, s[46:47]
	s_cbranch_vccz .LBB0_503
	s_cmp_eq_u32 s25, 0x800
	s_cbranch_scc0 .LBB0_503
	s_add_u32 s20, s38, 0x0
	s_addc_u32 s21, s39, 0
	v_lshl_add_u64 v[94:95], s[20:21], 0, v[146:147]
	global_load_dwordx4 v[60:63], v[94:95], off
	global_load_dwordx4 v[64:67], v[94:95], off offset:1024
	global_load_dwordx4 v[68:71], v[94:95], off offset:2048
	global_load_dwordx4 v[72:75], v[94:95], off offset:3072
	s_add_u32 s20, s20, 0x1000
	s_addc_u32 s21, s21, 0
	v_lshl_add_u64 v[94:95], s[20:21], 0, v[146:147]
	global_load_dwordx4 v[76:79], v[94:95], off
	global_load_dwordx4 v[80:83], v[94:95], off offset:1024
	global_load_dwordx4 v[84:87], v[94:95], off offset:2048
	global_load_dwordx4 v[88:91], v[94:95], off offset:3072
	v_add_u32_e32 v58, 0x1000, v96
	v_mov_b32_e32 v59, v147
	v_lshlrev_b64 v[94:95], 12, v[58:59]
	v_lshl_add_u64 v[94:95], s[34:35], 0, v[94:95]
	v_lshl_add_u64 v[94:95], v[94:95], 0, v[146:147]
	global_load_dwordx4 v[112:115], v[94:95], off
	global_load_dwordx4 v[116:119], v[94:95], off offset:1024
	global_load_dwordx4 v[120:123], v[94:95], off offset:2048
	global_load_dwordx4 v[124:127], v[94:95], off offset:3072
	v_add_u32_e32 v58, 0x1800, v96
	v_mov_b32_e32 v59, v147
	v_lshlrev_b64 v[94:95], 12, v[58:59]
	v_lshl_add_u64 v[94:95], s[34:35], 0, v[94:95]
	v_lshl_add_u64 v[94:95], v[94:95], 0, v[146:147]
	global_load_dwordx4 v[128:131], v[94:95], off
	global_load_dwordx4 v[132:135], v[94:95], off offset:1024
	global_load_dwordx4 v[136:139], v[94:95], off offset:2048
	global_load_dwordx4 v[140:143], v[94:95], off offset:3072
	s_waitcnt vmcnt(8)
	v_pk_add_f32 v[76:77], v[76:77], 1.0 op_sel_hi:[1,0]
	v_pk_add_f32 v[78:79], v[78:79], 1.0 op_sel_hi:[1,0]
	v_pk_add_f32 v[80:81], v[80:81], 1.0 op_sel_hi:[1,0]
	v_pk_add_f32 v[82:83], v[82:83], 1.0 op_sel_hi:[1,0]
	v_pk_add_f32 v[84:85], v[84:85], 1.0 op_sel_hi:[1,0]
	v_pk_add_f32 v[86:87], v[86:87], 1.0 op_sel_hi:[1,0]
	v_pk_add_f32 v[88:89], v[88:89], 1.0 op_sel_hi:[1,0]
	v_pk_add_f32 v[90:91], v[90:91], 1.0 op_sel_hi:[1,0]
	v_pk_mul_f32 v[52:53], v[28:29], v[28:29]
	v_pk_mul_f32 v[54:55], v[30:31], v[30:31]
	v_pk_fma_f32 v[52:53], v[24:25], v[24:25], v[52:53]
	v_pk_fma_f32 v[54:55], v[26:27], v[26:27], v[54:55]
	v_pk_fma_f32 v[52:53], v[20:21], v[20:21], v[52:53]
	v_pk_fma_f32 v[54:55], v[22:23], v[22:23], v[54:55]
	v_pk_fma_f32 v[52:53], v[16:17], v[16:17], v[52:53]
	v_pk_fma_f32 v[54:55], v[18:19], v[18:19], v[54:55]
	v_pk_add_f32 v[52:53], v[52:53], v[54:55]
	s_add_u32 s20, s38, 0x9000
	s_addc_u32 s21, s39, 0
	v_lshl_add_u64 v[94:95], s[20:21], 0, v[146:147]
	global_load_dwordx4 v[158:161], v[94:95], off
	global_load_dwordx4 v[162:165], v[94:95], off offset:1024
	global_load_dwordx4 v[166:169], v[94:95], off offset:2048
	global_load_dwordx4 v[170:173], v[94:95], off offset:3072
	s_add_u32 s20, s20, 0x1000
	s_addc_u32 s21, s21, 0
	v_lshl_add_u64 v[94:95], s[20:21], 0, v[146:147]
	global_load_dwordx4 v[174:177], v[94:95], off
	global_load_dwordx4 v[178:181], v[94:95], off offset:1024
	global_load_dwordx4 v[182:185], v[94:95], off offset:2048
	global_load_dwordx4 v[186:189], v[94:95], off offset:3072
	v_add_f32_e32 v97, v52, v53
	s_nop 1
	v_add_f32_dpp v97, v97, v97 quad_perm:[1,0,3,2] row_mask:0xf bank_mask:0xf
	s_nop 1
	v_add_f32_dpp v97, v97, v97 quad_perm:[2,3,0,1] row_mask:0xf bank_mask:0xf
	s_nop 1
	v_add_f32_dpp v97, v97, v97 row_ror:4 row_mask:0xf bank_mask:0xf
	s_nop 1
	v_add_f32_dpp v97, v97, v97 row_ror:8 row_mask:0xf bank_mask:0xf
	ds_bpermute_b32 v103, v108, v97
	v_add_u32_e32 v58, 0x0, v96
	v_mov_b32_e32 v59, v147
	v_lshlrev_b64 v[92:93], 11, v[58:59]
	v_lshl_add_u64 v[92:93], v[100:101], 0, v[92:93]
	s_waitcnt lgkmcnt(0)
	v_add_f32_e32 v103, v97, v103
	ds_bpermute_b32 v106, v109, v103
	s_waitcnt lgkmcnt(0)
; DI unsigned pk2(float lo, float hi) { const f32x2 v = {lo, hi}; const hbf16x2 b = __builtin_convertvector(v, hbf16x2); return __builtin_bit_cast(unsigned, b); }
; DI void norm_phase(const Ctx& a, int layer, int sub, bool first, const float* P, int nsl, int nrows) {
;     ...
; #pragma unroll
;         for (int j = 0; j < 4; ++j) ss += (v[j][0] * v[j][0] + v[j][1] * v[j][1]) + (v[j][2] * v[j][2] + v[j][3] * v[j][3]);
;         const float rstd = 1.f / sqrtf(wave_sum(ss, lane) * (1.f / 1024.f) + 1e-6f);
; #pragma unroll
;         for (int j = 0; j < 4; ++j) {
;             const int c = 4 * lane + 256 * j;
;             if ((first && row >= ML) || fold) *(f32x4*)(H + (size_t)row * 1024 + c) = v[j];
;             f32x4 y = v[j] * rstd * gg[j]; y = y * sc[j] + sh[j];
;             u32x2 w; w.x = pk2(y[0], y[1]); w.y = pk2(y[2], y[3]);
;             *(u32x2*)(XN + (size_t)row * 1024 + c) = w;
;         }
	v_add_f32_e32 v97, v103, v106
	v_fmamk_f32 v97, v97, 0x3a800000, v203
	v_mul_f32_e32 v103, 0x4f800000, v97
	v_cmp_gt_f32_e32 vcc, s26, v97
	s_nop 1
	v_cndmask_b32_e32 v97, v97, v103, vcc
	v_sqrt_f32_e32 v103, v97
	s_nop 0
	v_add_u32_e32 v106, -1, v103
	v_fma_f32 v111, -v106, v103, v97
	v_add_u32_e32 v107, 1, v103
	v_cmp_ge_f32_e64 s[42:43], 0, v111
	s_nop 1
	v_cndmask_b32_e64 v106, v103, v106, s[42:43]
	v_fma_f32 v103, -v107, v103, v97
	v_cmp_lt_f32_e64 s[42:43], 0, v103
	s_nop 1
	v_cndmask_b32_e64 v103, v106, v107, s[42:43]
	v_mul_f32_e32 v106, 0x37800000, v103
	v_cndmask_b32_e32 v103, v103, v106, vcc
	v_cmp_class_f32_e32 vcc, v97, v201
	s_nop 1
	v_cndmask_b32_e32 v97, v103, v97, vcc
	v_div_scale_f32 v103, s[30:31], v97, v97, 1.0
	v_rcp_f32_e32 v106, v103
	s_nop 0
	v_fma_f32 v107, -v103, v106, 1.0
	v_fmac_f32_e32 v106, v107, v106
	v_div_scale_f32 v107, vcc, 1.0, v97, 1.0
	v_mul_f32_e32 v111, v107, v106
	v_fma_f32 v45, -v103, v111, v107
	v_fmac_f32_e32 v111, v45, v106
	v_fma_f32 v103, -v103, v111, v107
	v_div_fmas_f32 v103, v103, v106, v111
	v_div_fixup_f32 v106, v103, v97, 1.0
	v_mov_b32_e32 v107, v106
	v_pk_mul_f32 v[28:29], v[28:29], v[106:107]
	v_pk_mul_f32 v[30:31], v[30:31], v[106:107]
	v_pk_mul_f32 v[28:29], v[0:1], v[28:29]
	v_pk_mul_f32 v[30:31], v[2:3], v[30:31]
	v_pk_fma_f32 v[28:29], v[76:77], v[28:29], v[60:61]
	v_pk_fma_f32 v[30:31], v[78:79], v[30:31], v[62:63]
	v_cvt_pk_bf16_f32 v54, v28, v29
	v_cvt_pk_bf16_f32 v55, v30, v31
	global_store_dwordx2 v[92:93], v[54:55], off
	v_pk_mul_f32 v[24:25], v[24:25], v[106:107]
	v_pk_mul_f32 v[26:27], v[26:27], v[106:107]
	v_pk_mul_f32 v[24:25], v[4:5], v[24:25]
	v_pk_mul_f32 v[26:27], v[6:7], v[26:27]
	v_pk_fma_f32 v[24:25], v[80:81], v[24:25], v[64:65]
	v_pk_fma_f32 v[26:27], v[82:83], v[26:27], v[66:67]
	v_cvt_pk_bf16_f32 v56, v24, v25
	v_cvt_pk_bf16_f32 v57, v26, v27
	global_store_dwordx2 v[92:93], v[56:57], off offset:512
	v_pk_mul_f32 v[20:21], v[20:21], v[106:107]
	v_pk_mul_f32 v[22:23], v[22:23], v[106:107]
	v_pk_mul_f32 v[20:21], v[8:9], v[20:21]
	v_pk_mul_f32 v[22:23], v[10:11], v[22:23]
	v_pk_fma_f32 v[20:21], v[84:85], v[20:21], v[68:69]
	v_pk_fma_f32 v[22:23], v[86:87], v[22:23], v[70:71]
	v_cvt_pk_bf16_f32 v54, v20, v21
	v_cvt_pk_bf16_f32 v55, v22, v23
	global_store_dwordx2 v[92:93], v[54:55], off offset:1024
	v_pk_mul_f32 v[16:17], v[16:17], v[106:107]
	v_pk_mul_f32 v[18:19], v[18:19], v[106:107]
	v_pk_mul_f32 v[16:17], v[12:13], v[16:17]
	v_pk_mul_f32 v[18:19], v[14:15], v[18:19]
	v_pk_fma_f32 v[16:17], v[88:89], v[16:17], v[72:73]
	v_pk_fma_f32 v[18:19], v[90:91], v[18:19], v[74:75]
	v_cvt_pk_bf16_f32 v56, v16, v17
	v_cvt_pk_bf16_f32 v57, v18, v19
	global_store_dwordx2 v[92:93], v[56:57], off offset:1536
	v_add_u32_e32 v58, 0x2000, v96
	v_mov_b32_e32 v59, v147
	v_lshlrev_b64 v[94:95], 12, v[58:59]
	v_lshl_add_u64 v[94:95], s[34:35], 0, v[94:95]
	v_lshl_add_u64 v[94:95], v[94:95], 0, v[146:147]
	global_load_dwordx4 v[28:31], v[94:95], off
	global_load_dwordx4 v[24:27], v[94:95], off offset:1024
	global_load_dwordx4 v[20:23], v[94:95], off offset:2048
	global_load_dwordx4 v[16:19], v[94:95], off offset:3072
	v_pk_mul_f32 v[52:53], v[36:37], v[36:37]
	v_pk_mul_f32 v[54:55], v[38:39], v[38:39]
	v_pk_fma_f32 v[52:53], v[40:41], v[40:41], v[52:53]
	v_pk_fma_f32 v[54:55], v[42:43], v[42:43], v[54:55]
	v_pk_fma_f32 v[52:53], v[48:49], v[48:49], v[52:53]
	v_pk_fma_f32 v[54:55], v[50:51], v[50:51], v[54:55]
	v_pk_fma_f32 v[52:53], v[32:33], v[32:33], v[52:53]
	v_pk_fma_f32 v[54:55], v[34:35], v[34:35], v[54:55]
	v_pk_add_f32 v[52:53], v[52:53], v[54:55]
	v_add_f32_e32 v97, v52, v53
	s_nop 1
	v_add_f32_dpp v97, v97, v97 quad_perm:[1,0,3,2] row_mask:0xf bank_mask:0xf
	s_nop 1
	v_add_f32_dpp v97, v97, v97 quad_perm:[2,3,0,1] row_mask:0xf bank_mask:0xf
	s_nop 1
	v_add_f32_dpp v97, v97, v97 row_ror:4 row_mask:0xf bank_mask:0xf
	s_nop 1
	v_add_f32_dpp v97, v97, v97 row_ror:8 row_mask:0xf bank_mask:0xf
	ds_bpermute_b32 v103, v108, v97
	v_add_u32_e32 v58, 0x800, v96
	v_mov_b32_e32 v59, v147
	v_lshlrev_b64 v[92:93], 11, v[58:59]
	v_lshl_add_u64 v[92:93], v[100:101], 0, v[92:93]
	s_waitcnt lgkmcnt(0)
	v_add_f32_e32 v103, v97, v103
	ds_bpermute_b32 v106, v109, v103
	s_waitcnt lgkmcnt(0)
	v_add_f32_e32 v97, v103, v106
	v_fmamk_f32 v97, v97, 0x3a800000, v203
	v_mul_f32_e32 v103, 0x4f800000, v97
	v_cmp_gt_f32_e32 vcc, s26, v97
	s_nop 1
	v_cndmask_b32_e32 v97, v97, v103, vcc
	v_sqrt_f32_e32 v103, v97
	s_nop 0
	v_add_u32_e32 v106, -1, v103
	v_fma_f32 v111, -v106, v103, v97
	v_add_u32_e32 v107, 1, v103
	v_cmp_ge_f32_e64 s[42:43], 0, v111
	s_nop 1
	v_cndmask_b32_e64 v106, v103, v106, s[42:43]
	v_fma_f32 v103, -v107, v103, v97
	v_cmp_lt_f32_e64 s[42:43], 0, v103
	s_nop 1
	v_cndmask_b32_e64 v103, v106, v107, s[42:43]
	v_mul_f32_e32 v106, 0x37800000, v103
	v_cndmask_b32_e32 v103, v103, v106, vcc
	v_cmp_class_f32_e32 vcc, v97, v201
	s_nop 1
	v_cndmask_b32_e32 v97, v103, v97, vcc
	v_div_scale_f32 v103, s[30:31], v97, v97, 1.0
	v_rcp_f32_e32 v106, v103
	s_nop 0
	v_fma_f32 v107, -v103, v106, 1.0
	v_fmac_f32_e32 v106, v107, v106
	v_div_scale_f32 v107, vcc, 1.0, v97, 1.0
	v_mul_f32_e32 v111, v107, v106
	v_fma_f32 v45, -v103, v111, v107
	v_fmac_f32_e32 v111, v45, v106
	v_fma_f32 v103, -v103, v111, v107
	v_div_fmas_f32 v103, v103, v106, v111
	v_div_fixup_f32 v106, v103, v97, 1.0
	v_mov_b32_e32 v107, v106
	v_pk_mul_f32 v[36:37], v[36:37], v[106:107]
	v_pk_mul_f32 v[38:39], v[38:39], v[106:107]
	v_pk_mul_f32 v[36:37], v[0:1], v[36:37]
	v_pk_mul_f32 v[38:39], v[2:3], v[38:39]
	v_pk_fma_f32 v[36:37], v[76:77], v[36:37], v[60:61]
	v_pk_fma_f32 v[38:39], v[78:79], v[38:39], v[62:63]
	v_cvt_pk_bf16_f32 v54, v36, v37
; DI unsigned pk2(float lo, float hi) { const f32x2 v = {lo, hi}; const hbf16x2 b = __builtin_convertvector(v, hbf16x2); return __builtin_bit_cast(unsigned, b); }
; DI void norm_phase(const Ctx& a, int layer, int sub, bool first, const float* P, int nsl, int nrows) {
;     ...
;         const int mr = row < ML ? (row >> 12) : 4;
;         if (mr != mr_cur) { mr_cur = mr;
; #pragma unroll
;             for (int j = 0; j < 4; ++j) { sh[j] = *(const f32x4*)(modl + (size_t)mr * MODW + 4 * lane + 256 * j); sc[j] = *(const f32x4*)(modl + (size_t)mr * MODW + 1024 + 4 * lane + 256 * j) + 1.f; } }
;         const bool fold = !first && row >= ML;
;         float ss = 0.f;
;         if (fold) {
;             for (int sl0 = 0; sl0 < nsl; sl0 += 4) {
;                 f32x4 t[4][4]; float wq[4];
; #pragma unroll
;                 for (int u = 0; u < 4; ++u) { const int sl = sl0 + u < nsl ? sl0 + u : nsl - 1; wq[u] = sl0 + u < nsl ? 1.f : 0.f;
; #pragma unroll
;                     for (int j = 0; j < 4; ++j) t[u][j] = *(const f32x4*)(P + ((size_t)sl * MC + (row - ML)) * D + 4 * lane + 256 * j); }
; #pragma unroll
;                 for (int u = 0; u < 4; ++u)
; #pragma unroll
;                     for (int j = 0; j < 4; ++j) v[j] = v[j] + t[u][j] * wq[u];
;             }
;         }
; #pragma unroll
;         for (int j = 0; j < 4; ++j) ss += (v[j][0] * v[j][0] + v[j][1] * v[j][1]) + (v[j][2] * v[j][2] + v[j][3] * v[j][3]);
;         const float rstd = 1.f / sqrtf(wave_sum(ss, lane) * (1.f / 1024.f) + 1e-6f);
; #pragma unroll
;         for (int j = 0; j < 4; ++j) {
;             const int c = 4 * lane + 256 * j;
;             if ((first && row >= ML) || fold) *(f32x4*)(H + (size_t)row * 1024 + c) = v[j];
;             f32x4 y = v[j] * rstd * gg[j]; y = y * sc[j] + sh[j];
;             u32x2 w; w.x = pk2(y[0], y[1]); w.y = pk2(y[2], y[3]);
;             *(u32x2*)(XN + (size_t)row * 1024 + c) = w;
;         }
	v_cvt_pk_bf16_f32 v55, v38, v39
	global_store_dwordx2 v[92:93], v[54:55], off
	v_pk_mul_f32 v[40:41], v[40:41], v[106:107]
	v_pk_mul_f32 v[42:43], v[42:43], v[106:107]
	v_pk_mul_f32 v[40:41], v[4:5], v[40:41]
	v_pk_mul_f32 v[42:43], v[6:7], v[42:43]
	v_pk_fma_f32 v[40:41], v[80:81], v[40:41], v[64:65]
	v_pk_fma_f32 v[42:43], v[82:83], v[42:43], v[66:67]
	v_cvt_pk_bf16_f32 v56, v40, v41
	v_cvt_pk_bf16_f32 v57, v42, v43
	global_store_dwordx2 v[92:93], v[56:57], off offset:512
	v_pk_mul_f32 v[48:49], v[48:49], v[106:107]
	v_pk_mul_f32 v[50:51], v[50:51], v[106:107]
	v_pk_mul_f32 v[48:49], v[8:9], v[48:49]
	v_pk_mul_f32 v[50:51], v[10:11], v[50:51]
	v_pk_fma_f32 v[48:49], v[84:85], v[48:49], v[68:69]
	v_pk_fma_f32 v[50:51], v[86:87], v[50:51], v[70:71]
	v_cvt_pk_bf16_f32 v54, v48, v49
	v_cvt_pk_bf16_f32 v55, v50, v51
	global_store_dwordx2 v[92:93], v[54:55], off offset:1024
	v_pk_mul_f32 v[32:33], v[32:33], v[106:107]
	v_pk_mul_f32 v[34:35], v[34:35], v[106:107]
	v_pk_mul_f32 v[32:33], v[12:13], v[32:33]
	v_pk_mul_f32 v[34:35], v[14:15], v[34:35]
	v_pk_fma_f32 v[32:33], v[88:89], v[32:33], v[72:73]
	v_pk_fma_f32 v[34:35], v[90:91], v[34:35], v[74:75]
	v_cvt_pk_bf16_f32 v56, v32, v33
	v_cvt_pk_bf16_f32 v57, v34, v35
	global_store_dwordx2 v[92:93], v[56:57], off offset:1536
	v_add_u32_e32 v58, 0x2800, v96
	v_mov_b32_e32 v59, v147
	v_lshlrev_b64 v[94:95], 12, v[58:59]
	v_lshl_add_u64 v[94:95], s[34:35], 0, v[94:95]
	v_lshl_add_u64 v[94:95], v[94:95], 0, v[146:147]
	global_load_dwordx4 v[36:39], v[94:95], off
	global_load_dwordx4 v[40:43], v[94:95], off offset:1024
	global_load_dwordx4 v[48:51], v[94:95], off offset:2048
	global_load_dwordx4 v[32:35], v[94:95], off offset:3072
	s_waitcnt vmcnt(16)
	v_pk_add_f32 v[174:175], v[174:175], 1.0 op_sel_hi:[1,0]
	v_pk_add_f32 v[176:177], v[176:177], 1.0 op_sel_hi:[1,0]
	v_pk_add_f32 v[178:179], v[178:179], 1.0 op_sel_hi:[1,0]
	v_pk_add_f32 v[180:181], v[180:181], 1.0 op_sel_hi:[1,0]
	v_pk_add_f32 v[182:183], v[182:183], 1.0 op_sel_hi:[1,0]
	v_pk_add_f32 v[184:185], v[184:185], 1.0 op_sel_hi:[1,0]
	v_pk_add_f32 v[186:187], v[186:187], 1.0 op_sel_hi:[1,0]
	v_pk_add_f32 v[188:189], v[188:189], 1.0 op_sel_hi:[1,0]
	v_pk_mul_f32 v[52:53], v[112:113], v[112:113]
	v_pk_mul_f32 v[54:55], v[114:115], v[114:115]
	v_pk_fma_f32 v[52:53], v[116:117], v[116:117], v[52:53]
	v_pk_fma_f32 v[54:55], v[118:119], v[118:119], v[54:55]
	v_pk_fma_f32 v[52:53], v[120:121], v[120:121], v[52:53]
	v_pk_fma_f32 v[54:55], v[122:123], v[122:123], v[54:55]
	v_pk_fma_f32 v[52:53], v[124:125], v[124:125], v[52:53]
	v_pk_fma_f32 v[54:55], v[126:127], v[126:127], v[54:55]
	v_pk_add_f32 v[52:53], v[52:53], v[54:55]
	s_add_u32 s20, s38, 0x12000
	s_addc_u32 s21, s39, 0
	v_lshl_add_u64 v[94:95], s[20:21], 0, v[146:147]
	global_load_dwordx4 v[60:63], v[94:95], off
	global_load_dwordx4 v[64:67], v[94:95], off offset:1024
	global_load_dwordx4 v[68:71], v[94:95], off offset:2048
	global_load_dwordx4 v[72:75], v[94:95], off offset:3072
	s_add_u32 s20, s20, 0x1000
	s_addc_u32 s21, s21, 0
	v_lshl_add_u64 v[94:95], s[20:21], 0, v[146:147]
	global_load_dwordx4 v[76:79], v[94:95], off
	global_load_dwordx4 v[80:83], v[94:95], off offset:1024
	global_load_dwordx4 v[84:87], v[94:95], off offset:2048
	global_load_dwordx4 v[88:91], v[94:95], off offset:3072
	v_add_f32_e32 v97, v52, v53
	s_nop 1
	v_add_f32_dpp v97, v97, v97 quad_perm:[1,0,3,2] row_mask:0xf bank_mask:0xf
	s_nop 1
	v_add_f32_dpp v97, v97, v97 quad_perm:[2,3,0,1] row_mask:0xf bank_mask:0xf
	s_nop 1
	v_add_f32_dpp v97, v97, v97 row_ror:4 row_mask:0xf bank_mask:0xf
	s_nop 1
	v_add_f32_dpp v97, v97, v97 row_ror:8 row_mask:0xf bank_mask:0xf
	ds_bpermute_b32 v103, v108, v97
	v_add_u32_e32 v58, 0x1000, v96
	v_mov_b32_e32 v59, v147
	v_lshlrev_b64 v[92:93], 11, v[58:59]
	v_lshl_add_u64 v[92:93], v[100:101], 0, v[92:93]
	s_waitcnt lgkmcnt(0)
	v_add_f32_e32 v103, v97, v103
	ds_bpermute_b32 v106, v109, v103
	s_waitcnt lgkmcnt(0)
	v_add_f32_e32 v97, v103, v106
	v_fmamk_f32 v97, v97, 0x3a800000, v203
	v_mul_f32_e32 v103, 0x4f800000, v97
	v_cmp_gt_f32_e32 vcc, s26, v97
	s_nop 1
	v_cndmask_b32_e32 v97, v97, v103, vcc
	v_sqrt_f32_e32 v103, v97
	s_nop 0
	v_add_u32_e32 v106, -1, v103
	v_fma_f32 v111, -v106, v103, v97
	v_add_u32_e32 v107, 1, v103
	v_cmp_ge_f32_e64 s[42:43], 0, v111
	s_nop 1
	v_cndmask_b32_e64 v106, v103, v106, s[42:43]
	v_fma_f32 v103, -v107, v103, v97
	v_cmp_lt_f32_e64 s[42:43], 0, v103
	s_nop 1
	v_cndmask_b32_e64 v103, v106, v107, s[42:43]
	v_mul_f32_e32 v106, 0x37800000, v103
	v_cndmask_b32_e32 v103, v103, v106, vcc
	v_cmp_class_f32_e32 vcc, v97, v201
	s_nop 1
	v_cndmask_b32_e32 v97, v103, v97, vcc
	v_div_scale_f32 v103, s[30:31], v97, v97, 1.0
	v_rcp_f32_e32 v106, v103
	s_nop 0
	v_fma_f32 v107, -v103, v106, 1.0
	v_fmac_f32_e32 v106, v107, v106
	v_div_scale_f32 v107, vcc, 1.0, v97, 1.0
	v_mul_f32_e32 v111, v107, v106
	v_fma_f32 v45, -v103, v111, v107
	v_fmac_f32_e32 v111, v45, v106
	v_fma_f32 v103, -v103, v111, v107
	v_div_fmas_f32 v103, v103, v106, v111
	v_div_fixup_f32 v106, v103, v97, 1.0
	v_mov_b32_e32 v107, v106
	v_pk_mul_f32 v[112:113], v[112:113], v[106:107]
	v_pk_mul_f32 v[114:115], v[114:115], v[106:107]
	v_pk_mul_f32 v[112:113], v[0:1], v[112:113]
	v_pk_mul_f32 v[114:115], v[2:3], v[114:115]
	v_pk_fma_f32 v[112:113], v[174:175], v[112:113], v[158:159]
	v_pk_fma_f32 v[114:115], v[176:177], v[114:115], v[160:161]
	v_cvt_pk_bf16_f32 v54, v112, v113
	v_cvt_pk_bf16_f32 v55, v114, v115
	global_store_dwordx2 v[92:93], v[54:55], off
	v_pk_mul_f32 v[116:117], v[116:117], v[106:107]
	v_pk_mul_f32 v[118:119], v[118:119], v[106:107]
	v_pk_mul_f32 v[116:117], v[4:5], v[116:117]
; DI unsigned pk2(float lo, float hi) { const f32x2 v = {lo, hi}; const hbf16x2 b = __builtin_convertvector(v, hbf16x2); return __builtin_bit_cast(unsigned, b); }
; DI void norm_phase(const Ctx& a, int layer, int sub, bool first, const float* P, int nsl, int nrows) {
;     ...
; #pragma unroll
;         for (int j = 0; j < 4; ++j) ss += (v[j][0] * v[j][0] + v[j][1] * v[j][1]) + (v[j][2] * v[j][2] + v[j][3] * v[j][3]);
;         const float rstd = 1.f / sqrtf(wave_sum(ss, lane) * (1.f / 1024.f) + 1e-6f);
; #pragma unroll
;         for (int j = 0; j < 4; ++j) {
;             const int c = 4 * lane + 256 * j;
;             if ((first && row >= ML) || fold) *(f32x4*)(H + (size_t)row * 1024 + c) = v[j];
;             f32x4 y = v[j] * rstd * gg[j]; y = y * sc[j] + sh[j];
;             u32x2 w; w.x = pk2(y[0], y[1]); w.y = pk2(y[2], y[3]);
;             *(u32x2*)(XN + (size_t)row * 1024 + c) = w;
;         }
	v_pk_mul_f32 v[118:119], v[6:7], v[118:119]
	v_pk_fma_f32 v[116:117], v[178:179], v[116:117], v[162:163]
	v_pk_fma_f32 v[118:119], v[180:181], v[118:119], v[164:165]
	v_cvt_pk_bf16_f32 v56, v116, v117
	v_cvt_pk_bf16_f32 v57, v118, v119
	global_store_dwordx2 v[92:93], v[56:57], off offset:512
	v_pk_mul_f32 v[120:121], v[120:121], v[106:107]
	v_pk_mul_f32 v[122:123], v[122:123], v[106:107]
	v_pk_mul_f32 v[120:121], v[8:9], v[120:121]
	v_pk_mul_f32 v[122:123], v[10:11], v[122:123]
	v_pk_fma_f32 v[120:121], v[182:183], v[120:121], v[166:167]
	v_pk_fma_f32 v[122:123], v[184:185], v[122:123], v[168:169]
	v_cvt_pk_bf16_f32 v54, v120, v121
	v_cvt_pk_bf16_f32 v55, v122, v123
	global_store_dwordx2 v[92:93], v[54:55], off offset:1024
	v_pk_mul_f32 v[124:125], v[124:125], v[106:107]
	v_pk_mul_f32 v[126:127], v[126:127], v[106:107]
	v_pk_mul_f32 v[124:125], v[12:13], v[124:125]
	v_pk_mul_f32 v[126:127], v[14:15], v[126:127]
	v_pk_fma_f32 v[124:125], v[186:187], v[124:125], v[170:171]
	v_pk_fma_f32 v[126:127], v[188:189], v[126:127], v[172:173]
	v_cvt_pk_bf16_f32 v56, v124, v125
	v_cvt_pk_bf16_f32 v57, v126, v127
	global_store_dwordx2 v[92:93], v[56:57], off offset:1536
	v_add_u32_e32 v58, 0x3000, v96
	v_mov_b32_e32 v59, v147
	v_lshlrev_b64 v[94:95], 12, v[58:59]
	v_lshl_add_u64 v[94:95], s[34:35], 0, v[94:95]
	v_lshl_add_u64 v[94:95], v[94:95], 0, v[146:147]
	global_load_dwordx4 v[112:115], v[94:95], off
	global_load_dwordx4 v[116:119], v[94:95], off offset:1024
	global_load_dwordx4 v[120:123], v[94:95], off offset:2048
	global_load_dwordx4 v[124:127], v[94:95], off offset:3072
	v_pk_mul_f32 v[52:53], v[128:129], v[128:129]
	v_pk_mul_f32 v[54:55], v[130:131], v[130:131]
	v_pk_fma_f32 v[52:53], v[132:133], v[132:133], v[52:53]
	v_pk_fma_f32 v[54:55], v[134:135], v[134:135], v[54:55]
	v_pk_fma_f32 v[52:53], v[136:137], v[136:137], v[52:53]
	v_pk_fma_f32 v[54:55], v[138:139], v[138:139], v[54:55]
	v_pk_fma_f32 v[52:53], v[140:141], v[140:141], v[52:53]
	v_pk_fma_f32 v[54:55], v[142:143], v[142:143], v[54:55]
	v_pk_add_f32 v[52:53], v[52:53], v[54:55]
	v_add_f32_e32 v97, v52, v53
	s_nop 1
	v_add_f32_dpp v97, v97, v97 quad_perm:[1,0,3,2] row_mask:0xf bank_mask:0xf
	s_nop 1
	v_add_f32_dpp v97, v97, v97 quad_perm:[2,3,0,1] row_mask:0xf bank_mask:0xf
	s_nop 1
	v_add_f32_dpp v97, v97, v97 row_ror:4 row_mask:0xf bank_mask:0xf
	s_nop 1
	v_add_f32_dpp v97, v97, v97 row_ror:8 row_mask:0xf bank_mask:0xf
	ds_bpermute_b32 v103, v108, v97
	v_add_u32_e32 v58, 0x1800, v96
	v_mov_b32_e32 v59, v147
	v_lshlrev_b64 v[92:93], 11, v[58:59]
	v_lshl_add_u64 v[92:93], v[100:101], 0, v[92:93]
	s_waitcnt lgkmcnt(0)
	v_add_f32_e32 v103, v97, v103
	ds_bpermute_b32 v106, v109, v103
	s_waitcnt lgkmcnt(0)
	v_add_f32_e32 v97, v103, v106
	v_fmamk_f32 v97, v97, 0x3a800000, v203
	v_mul_f32_e32 v103, 0x4f800000, v97
	v_cmp_gt_f32_e32 vcc, s26, v97
	s_nop 1
	v_cndmask_b32_e32 v97, v97, v103, vcc
	v_sqrt_f32_e32 v103, v97
	s_nop 0
	v_add_u32_e32 v106, -1, v103
	v_fma_f32 v111, -v106, v103, v97
	v_add_u32_e32 v107, 1, v103
	v_cmp_ge_f32_e64 s[42:43], 0, v111
	s_nop 1
	v_cndmask_b32_e64 v106, v103, v106, s[42:43]
	v_fma_f32 v103, -v107, v103, v97
	v_cmp_lt_f32_e64 s[42:43], 0, v103
	s_nop 1
	v_cndmask_b32_e64 v103, v106, v107, s[42:43]
	v_mul_f32_e32 v106, 0x37800000, v103
	v_cndmask_b32_e32 v103, v103, v106, vcc
	v_cmp_class_f32_e32 vcc, v97, v201
	s_nop 1
	v_cndmask_b32_e32 v97, v103, v97, vcc
	v_div_scale_f32 v103, s[30:31], v97, v97, 1.0
	v_rcp_f32_e32 v106, v103
	s_nop 0
	v_fma_f32 v107, -v103, v106, 1.0
	v_fmac_f32_e32 v106, v107, v106
	v_div_scale_f32 v107, vcc, 1.0, v97, 1.0
	v_mul_f32_e32 v111, v107, v106
	v_fma_f32 v45, -v103, v111, v107
	v_fmac_f32_e32 v111, v45, v106
	v_fma_f32 v103, -v103, v111, v107
	v_div_fmas_f32 v103, v103, v106, v111
	v_div_fixup_f32 v106, v103, v97, 1.0
	v_mov_b32_e32 v107, v106
	v_pk_mul_f32 v[128:129], v[128:129], v[106:107]
	v_pk_mul_f32 v[130:131], v[130:131], v[106:107]
	v_pk_mul_f32 v[128:129], v[0:1], v[128:129]
	v_pk_mul_f32 v[130:131], v[2:3], v[130:131]
	v_pk_fma_f32 v[128:129], v[174:175], v[128:129], v[158:159]
	v_pk_fma_f32 v[130:131], v[176:177], v[130:131], v[160:161]
	v_cvt_pk_bf16_f32 v54, v128, v129
	v_cvt_pk_bf16_f32 v55, v130, v131
	global_store_dwordx2 v[92:93], v[54:55], off
	v_pk_mul_f32 v[132:133], v[132:133], v[106:107]
	v_pk_mul_f32 v[134:135], v[134:135], v[106:107]
	v_pk_mul_f32 v[132:133], v[4:5], v[132:133]
	v_pk_mul_f32 v[134:135], v[6:7], v[134:135]
	v_pk_fma_f32 v[132:133], v[178:179], v[132:133], v[162:163]
	v_pk_fma_f32 v[134:135], v[180:181], v[134:135], v[164:165]
	v_cvt_pk_bf16_f32 v56, v132, v133
	v_cvt_pk_bf16_f32 v57, v134, v135
	global_store_dwordx2 v[92:93], v[56:57], off offset:512
	v_pk_mul_f32 v[136:137], v[136:137], v[106:107]
	v_pk_mul_f32 v[138:139], v[138:139], v[106:107]
	v_pk_mul_f32 v[136:137], v[8:9], v[136:137]
	v_pk_mul_f32 v[138:139], v[10:11], v[138:139]
	v_pk_fma_f32 v[136:137], v[182:183], v[136:137], v[166:167]
	v_pk_fma_f32 v[138:139], v[184:185], v[138:139], v[168:169]
	v_cvt_pk_bf16_f32 v54, v136, v137
	v_cvt_pk_bf16_f32 v55, v138, v139
	global_store_dwordx2 v[92:93], v[54:55], off offset:1024
	v_pk_mul_f32 v[140:141], v[140:141], v[106:107]
	v_pk_mul_f32 v[142:143], v[142:143], v[106:107]
	v_pk_mul_f32 v[140:141], v[12:13], v[140:141]
	v_pk_mul_f32 v[142:143], v[14:15], v[142:143]
	v_pk_fma_f32 v[140:141], v[186:187], v[140:141], v[170:171]
	v_pk_fma_f32 v[142:143], v[188:189], v[142:143], v[172:173]
	v_cvt_pk_bf16_f32 v56, v140, v141
	v_cvt_pk_bf16_f32 v57, v142, v143
	global_store_dwordx2 v[92:93], v[56:57], off offset:1536
	v_add_u32_e32 v58, 0x3800, v96
	v_mov_b32_e32 v59, v147
	v_lshlrev_b64 v[94:95], 12, v[58:59]
	v_lshl_add_u64 v[94:95], s[34:35], 0, v[94:95]
	v_lshl_add_u64 v[94:95], v[94:95], 0, v[146:147]
	global_load_dwordx4 v[128:131], v[94:95], off
	global_load_dwordx4 v[132:135], v[94:95], off offset:1024
	global_load_dwordx4 v[136:139], v[94:95], off offset:2048
	global_load_dwordx4 v[140:143], v[94:95], off offset:3072
	s_waitcnt vmcnt(16)
; DI unsigned pk2(float lo, float hi) { const f32x2 v = {lo, hi}; const hbf16x2 b = __builtin_convertvector(v, hbf16x2); return __builtin_bit_cast(unsigned, b); }
; DI void norm_phase(const Ctx& a, int layer, int sub, bool first, const float* P, int nsl, int nrows) {
;     ...
;         const int mr = row < ML ? (row >> 12) : 4;
;         if (mr != mr_cur) { mr_cur = mr;
; #pragma unroll
;             for (int j = 0; j < 4; ++j) { sh[j] = *(const f32x4*)(modl + (size_t)mr * MODW + 4 * lane + 256 * j); sc[j] = *(const f32x4*)(modl + (size_t)mr * MODW + 1024 + 4 * lane + 256 * j) + 1.f; } }
;         const bool fold = !first && row >= ML;
;         float ss = 0.f;
;         if (fold) {
;             for (int sl0 = 0; sl0 < nsl; sl0 += 4) {
;                 f32x4 t[4][4]; float wq[4];
; #pragma unroll
;                 for (int u = 0; u < 4; ++u) { const int sl = sl0 + u < nsl ? sl0 + u : nsl - 1; wq[u] = sl0 + u < nsl ? 1.f : 0.f;
; #pragma unroll
;                     for (int j = 0; j < 4; ++j) t[u][j] = *(const f32x4*)(P + ((size_t)sl * MC + (row - ML)) * D + 4 * lane + 256 * j); }
; #pragma unroll
;                 for (int u = 0; u < 4; ++u)
; #pragma unroll
;                     for (int j = 0; j < 4; ++j) v[j] = v[j] + t[u][j] * wq[u];
;             }
;         }
; #pragma unroll
;         for (int j = 0; j < 4; ++j) ss += (v[j][0] * v[j][0] + v[j][1] * v[j][1]) + (v[j][2] * v[j][2] + v[j][3] * v[j][3]);
;         const float rstd = 1.f / sqrtf(wave_sum(ss, lane) * (1.f / 1024.f) + 1e-6f);
; #pragma unroll
;         for (int j = 0; j < 4; ++j) {
;             const int c = 4 * lane + 256 * j;
;             if ((first && row >= ML) || fold) *(f32x4*)(H + (size_t)row * 1024 + c) = v[j];
;             f32x4 y = v[j] * rstd * gg[j]; y = y * sc[j] + sh[j];
;             u32x2 w; w.x = pk2(y[0], y[1]); w.y = pk2(y[2], y[3]);
;             *(u32x2*)(XN + (size_t)row * 1024 + c) = w;
;         }
	v_pk_add_f32 v[76:77], v[76:77], 1.0 op_sel_hi:[1,0]
	v_pk_add_f32 v[78:79], v[78:79], 1.0 op_sel_hi:[1,0]
	v_pk_add_f32 v[80:81], v[80:81], 1.0 op_sel_hi:[1,0]
	v_pk_add_f32 v[82:83], v[82:83], 1.0 op_sel_hi:[1,0]
	v_pk_add_f32 v[84:85], v[84:85], 1.0 op_sel_hi:[1,0]
	v_pk_add_f32 v[86:87], v[86:87], 1.0 op_sel_hi:[1,0]
	v_pk_add_f32 v[88:89], v[88:89], 1.0 op_sel_hi:[1,0]
	v_pk_add_f32 v[90:91], v[90:91], 1.0 op_sel_hi:[1,0]
	v_pk_mul_f32 v[52:53], v[28:29], v[28:29]
	v_pk_mul_f32 v[54:55], v[30:31], v[30:31]
	v_pk_fma_f32 v[52:53], v[24:25], v[24:25], v[52:53]
	v_pk_fma_f32 v[54:55], v[26:27], v[26:27], v[54:55]
	v_pk_fma_f32 v[52:53], v[20:21], v[20:21], v[52:53]
	v_pk_fma_f32 v[54:55], v[22:23], v[22:23], v[54:55]
	v_pk_fma_f32 v[52:53], v[16:17], v[16:17], v[52:53]
	v_pk_fma_f32 v[54:55], v[18:19], v[18:19], v[54:55]
	v_pk_add_f32 v[52:53], v[52:53], v[54:55]
	s_add_u32 s20, s38, 0x1b000
	s_addc_u32 s21, s39, 0
	v_lshl_add_u64 v[94:95], s[20:21], 0, v[146:147]
	global_load_dwordx4 v[158:161], v[94:95], off
	global_load_dwordx4 v[162:165], v[94:95], off offset:1024
	global_load_dwordx4 v[166:169], v[94:95], off offset:2048
	global_load_dwordx4 v[170:173], v[94:95], off offset:3072
	s_add_u32 s20, s20, 0x1000
	s_addc_u32 s21, s21, 0
	v_lshl_add_u64 v[94:95], s[20:21], 0, v[146:147]
	global_load_dwordx4 v[174:177], v[94:95], off
	global_load_dwordx4 v[178:181], v[94:95], off offset:1024
	global_load_dwordx4 v[182:185], v[94:95], off offset:2048
	global_load_dwordx4 v[186:189], v[94:95], off offset:3072
	v_add_f32_e32 v97, v52, v53
	s_nop 1
	v_add_f32_dpp v97, v97, v97 quad_perm:[1,0,3,2] row_mask:0xf bank_mask:0xf
	s_nop 1
	v_add_f32_dpp v97, v97, v97 quad_perm:[2,3,0,1] row_mask:0xf bank_mask:0xf
	s_nop 1
	v_add_f32_dpp v97, v97, v97 row_ror:4 row_mask:0xf bank_mask:0xf
	s_nop 1
	v_add_f32_dpp v97, v97, v97 row_ror:8 row_mask:0xf bank_mask:0xf
	ds_bpermute_b32 v103, v108, v97
	v_add_u32_e32 v58, 0x2000, v96
	v_mov_b32_e32 v59, v147
	v_lshlrev_b64 v[92:93], 11, v[58:59]
	v_lshl_add_u64 v[92:93], v[100:101], 0, v[92:93]
	s_waitcnt lgkmcnt(0)
	v_add_f32_e32 v103, v97, v103
	ds_bpermute_b32 v106, v109, v103
	s_waitcnt lgkmcnt(0)
	v_add_f32_e32 v97, v103, v106
	v_fmamk_f32 v97, v97, 0x3a800000, v203
	v_mul_f32_e32 v103, 0x4f800000, v97
	v_cmp_gt_f32_e32 vcc, s26, v97
	s_nop 1
	v_cndmask_b32_e32 v97, v97, v103, vcc
	v_sqrt_f32_e32 v103, v97
	s_nop 0
	v_add_u32_e32 v106, -1, v103
	v_fma_f32 v111, -v106, v103, v97
	v_add_u32_e32 v107, 1, v103
	v_cmp_ge_f32_e64 s[42:43], 0, v111
	s_nop 1
	v_cndmask_b32_e64 v106, v103, v106, s[42:43]
	v_fma_f32 v103, -v107, v103, v97
	v_cmp_lt_f32_e64 s[42:43], 0, v103
	s_nop 1
	v_cndmask_b32_e64 v103, v106, v107, s[42:43]
	v_mul_f32_e32 v106, 0x37800000, v103
	v_cndmask_b32_e32 v103, v103, v106, vcc
	v_cmp_class_f32_e32 vcc, v97, v201
	s_nop 1
	v_cndmask_b32_e32 v97, v103, v97, vcc
	v_div_scale_f32 v103, s[30:31], v97, v97, 1.0
	v_rcp_f32_e32 v106, v103
	s_nop 0
	v_fma_f32 v107, -v103, v106, 1.0
	v_fmac_f32_e32 v106, v107, v106
	v_div_scale_f32 v107, vcc, 1.0, v97, 1.0
	v_mul_f32_e32 v111, v107, v106
	v_fma_f32 v45, -v103, v111, v107
	v_fmac_f32_e32 v111, v45, v106
	v_fma_f32 v103, -v103, v111, v107
	v_div_fmas_f32 v103, v103, v106, v111
	v_div_fixup_f32 v106, v103, v97, 1.0
	v_mov_b32_e32 v107, v106
	v_pk_mul_f32 v[28:29], v[28:29], v[106:107]
	v_pk_mul_f32 v[30:31], v[30:31], v[106:107]
	v_pk_mul_f32 v[28:29], v[0:1], v[28:29]
	v_pk_mul_f32 v[30:31], v[2:3], v[30:31]
	v_pk_fma_f32 v[28:29], v[76:77], v[28:29], v[60:61]
	v_pk_fma_f32 v[30:31], v[78:79], v[30:31], v[62:63]
	v_cvt_pk_bf16_f32 v54, v28, v29
	v_cvt_pk_bf16_f32 v55, v30, v31
	global_store_dwordx2 v[92:93], v[54:55], off
	v_pk_mul_f32 v[24:25], v[24:25], v[106:107]
	v_pk_mul_f32 v[26:27], v[26:27], v[106:107]
	v_pk_mul_f32 v[24:25], v[4:5], v[24:25]
	v_pk_mul_f32 v[26:27], v[6:7], v[26:27]
	v_pk_fma_f32 v[24:25], v[80:81], v[24:25], v[64:65]
	v_pk_fma_f32 v[26:27], v[82:83], v[26:27], v[66:67]
	v_cvt_pk_bf16_f32 v56, v24, v25
	v_cvt_pk_bf16_f32 v57, v26, v27
	global_store_dwordx2 v[92:93], v[56:57], off offset:512
	v_pk_mul_f32 v[20:21], v[20:21], v[106:107]
	v_pk_mul_f32 v[22:23], v[22:23], v[106:107]
	v_pk_mul_f32 v[20:21], v[8:9], v[20:21]
	v_pk_mul_f32 v[22:23], v[10:11], v[22:23]
	v_pk_fma_f32 v[20:21], v[84:85], v[20:21], v[68:69]
	v_pk_fma_f32 v[22:23], v[86:87], v[22:23], v[70:71]
	v_cvt_pk_bf16_f32 v54, v20, v21
	v_cvt_pk_bf16_f32 v55, v22, v23
	global_store_dwordx2 v[92:93], v[54:55], off offset:1024
	v_pk_mul_f32 v[16:17], v[16:17], v[106:107]
	v_pk_mul_f32 v[18:19], v[18:19], v[106:107]
	v_pk_mul_f32 v[16:17], v[12:13], v[16:17]
	v_pk_mul_f32 v[18:19], v[14:15], v[18:19]
	v_pk_fma_f32 v[16:17], v[88:89], v[16:17], v[72:73]
	v_pk_fma_f32 v[18:19], v[90:91], v[18:19], v[74:75]
	v_cvt_pk_bf16_f32 v56, v16, v17
	v_cvt_pk_bf16_f32 v57, v18, v19
	global_store_dwordx2 v[92:93], v[56:57], off offset:1536
	v_pk_mul_f32 v[52:53], v[36:37], v[36:37]
	v_pk_mul_f32 v[54:55], v[38:39], v[38:39]
	v_pk_fma_f32 v[52:53], v[40:41], v[40:41], v[52:53]
	v_pk_fma_f32 v[54:55], v[42:43], v[42:43], v[54:55]
	v_pk_fma_f32 v[52:53], v[48:49], v[48:49], v[52:53]
	v_pk_fma_f32 v[54:55], v[50:51], v[50:51], v[54:55]
	v_pk_fma_f32 v[52:53], v[32:33], v[32:33], v[52:53]
	v_pk_fma_f32 v[54:55], v[34:35], v[34:35], v[54:55]
	v_pk_add_f32 v[52:53], v[52:53], v[54:55]
	v_add_f32_e32 v97, v52, v53
	s_nop 1
	v_add_f32_dpp v97, v97, v97 quad_perm:[1,0,3,2] row_mask:0xf bank_mask:0xf
	s_nop 1
	v_add_f32_dpp v97, v97, v97 quad_perm:[2,3,0,1] row_mask:0xf bank_mask:0xf
	s_nop 1
	v_add_f32_dpp v97, v97, v97 row_ror:4 row_mask:0xf bank_mask:0xf
	s_nop 1
	v_add_f32_dpp v97, v97, v97 row_ror:8 row_mask:0xf bank_mask:0xf
	ds_bpermute_b32 v103, v108, v97
	v_add_u32_e32 v58, 0x2800, v96
	v_mov_b32_e32 v59, v147
	v_lshlrev_b64 v[92:93], 11, v[58:59]
	v_lshl_add_u64 v[92:93], v[100:101], 0, v[92:93]
	s_waitcnt lgkmcnt(0)
; DI unsigned pk2(float lo, float hi) { const f32x2 v = {lo, hi}; const hbf16x2 b = __builtin_convertvector(v, hbf16x2); return __builtin_bit_cast(unsigned, b); }
; DI void norm_phase(const Ctx& a, int layer, int sub, bool first, const float* P, int nsl, int nrows) {
;     ...
; #pragma unroll
;         for (int j = 0; j < 4; ++j) ss += (v[j][0] * v[j][0] + v[j][1] * v[j][1]) + (v[j][2] * v[j][2] + v[j][3] * v[j][3]);
;         const float rstd = 1.f / sqrtf(wave_sum(ss, lane) * (1.f / 1024.f) + 1e-6f);
; #pragma unroll
;         for (int j = 0; j < 4; ++j) {
;             const int c = 4 * lane + 256 * j;
;             if ((first && row >= ML) || fold) *(f32x4*)(H + (size_t)row * 1024 + c) = v[j];
;             f32x4 y = v[j] * rstd * gg[j]; y = y * sc[j] + sh[j];
;             u32x2 w; w.x = pk2(y[0], y[1]); w.y = pk2(y[2], y[3]);
;             *(u32x2*)(XN + (size_t)row * 1024 + c) = w;
;         }
	v_add_f32_e32 v103, v97, v103
	ds_bpermute_b32 v106, v109, v103
	s_waitcnt lgkmcnt(0)
	v_add_f32_e32 v97, v103, v106
	v_fmamk_f32 v97, v97, 0x3a800000, v203
	v_mul_f32_e32 v103, 0x4f800000, v97
	v_cmp_gt_f32_e32 vcc, s26, v97
	s_nop 1
	v_cndmask_b32_e32 v97, v97, v103, vcc
	v_sqrt_f32_e32 v103, v97
	s_nop 0
	v_add_u32_e32 v106, -1, v103
	v_fma_f32 v111, -v106, v103, v97
	v_add_u32_e32 v107, 1, v103
	v_cmp_ge_f32_e64 s[42:43], 0, v111
	s_nop 1
	v_cndmask_b32_e64 v106, v103, v106, s[42:43]
	v_fma_f32 v103, -v107, v103, v97
	v_cmp_lt_f32_e64 s[42:43], 0, v103
	s_nop 1
	v_cndmask_b32_e64 v103, v106, v107, s[42:43]
	v_mul_f32_e32 v106, 0x37800000, v103
	v_cndmask_b32_e32 v103, v103, v106, vcc
	v_cmp_class_f32_e32 vcc, v97, v201
	s_nop 1
	v_cndmask_b32_e32 v97, v103, v97, vcc
	v_div_scale_f32 v103, s[30:31], v97, v97, 1.0
	v_rcp_f32_e32 v106, v103
	s_nop 0
	v_fma_f32 v107, -v103, v106, 1.0
	v_fmac_f32_e32 v106, v107, v106
	v_div_scale_f32 v107, vcc, 1.0, v97, 1.0
	v_mul_f32_e32 v111, v107, v106
	v_fma_f32 v45, -v103, v111, v107
	v_fmac_f32_e32 v111, v45, v106
	v_fma_f32 v103, -v103, v111, v107
	v_div_fmas_f32 v103, v103, v106, v111
	v_div_fixup_f32 v106, v103, v97, 1.0
	v_mov_b32_e32 v107, v106
	v_pk_mul_f32 v[36:37], v[36:37], v[106:107]
	v_pk_mul_f32 v[38:39], v[38:39], v[106:107]
	v_pk_mul_f32 v[36:37], v[0:1], v[36:37]
	v_pk_mul_f32 v[38:39], v[2:3], v[38:39]
	v_pk_fma_f32 v[36:37], v[76:77], v[36:37], v[60:61]
	v_pk_fma_f32 v[38:39], v[78:79], v[38:39], v[62:63]
	v_cvt_pk_bf16_f32 v54, v36, v37
	v_cvt_pk_bf16_f32 v55, v38, v39
	global_store_dwordx2 v[92:93], v[54:55], off
	v_pk_mul_f32 v[40:41], v[40:41], v[106:107]
	v_pk_mul_f32 v[42:43], v[42:43], v[106:107]
	v_pk_mul_f32 v[40:41], v[4:5], v[40:41]
	v_pk_mul_f32 v[42:43], v[6:7], v[42:43]
	v_pk_fma_f32 v[40:41], v[80:81], v[40:41], v[64:65]
	v_pk_fma_f32 v[42:43], v[82:83], v[42:43], v[66:67]
	v_cvt_pk_bf16_f32 v56, v40, v41
	v_cvt_pk_bf16_f32 v57, v42, v43
	global_store_dwordx2 v[92:93], v[56:57], off offset:512
	v_pk_mul_f32 v[48:49], v[48:49], v[106:107]
	v_pk_mul_f32 v[50:51], v[50:51], v[106:107]
	v_pk_mul_f32 v[48:49], v[8:9], v[48:49]
	v_pk_mul_f32 v[50:51], v[10:11], v[50:51]
	v_pk_fma_f32 v[48:49], v[84:85], v[48:49], v[68:69]
	v_pk_fma_f32 v[50:51], v[86:87], v[50:51], v[70:71]
	v_cvt_pk_bf16_f32 v54, v48, v49
	v_cvt_pk_bf16_f32 v55, v50, v51
	global_store_dwordx2 v[92:93], v[54:55], off offset:1024
	v_pk_mul_f32 v[32:33], v[32:33], v[106:107]
	v_pk_mul_f32 v[34:35], v[34:35], v[106:107]
	v_pk_mul_f32 v[32:33], v[12:13], v[32:33]
	v_pk_mul_f32 v[34:35], v[14:15], v[34:35]
	v_pk_fma_f32 v[32:33], v[88:89], v[32:33], v[72:73]
	v_pk_fma_f32 v[34:35], v[90:91], v[34:35], v[74:75]
	v_cvt_pk_bf16_f32 v56, v32, v33
	v_cvt_pk_bf16_f32 v57, v34, v35
	global_store_dwordx2 v[92:93], v[56:57], off offset:1536
	s_waitcnt vmcnt(8)
	v_pk_add_f32 v[174:175], v[174:175], 1.0 op_sel_hi:[1,0]
	v_pk_add_f32 v[176:177], v[176:177], 1.0 op_sel_hi:[1,0]
	v_pk_add_f32 v[178:179], v[178:179], 1.0 op_sel_hi:[1,0]
	v_pk_add_f32 v[180:181], v[180:181], 1.0 op_sel_hi:[1,0]
	v_pk_add_f32 v[182:183], v[182:183], 1.0 op_sel_hi:[1,0]
	v_pk_add_f32 v[184:185], v[184:185], 1.0 op_sel_hi:[1,0]
	v_pk_add_f32 v[186:187], v[186:187], 1.0 op_sel_hi:[1,0]
	v_pk_add_f32 v[188:189], v[188:189], 1.0 op_sel_hi:[1,0]
	v_pk_mul_f32 v[52:53], v[112:113], v[112:113]
	v_pk_mul_f32 v[54:55], v[114:115], v[114:115]
	v_pk_fma_f32 v[52:53], v[116:117], v[116:117], v[52:53]
	v_pk_fma_f32 v[54:55], v[118:119], v[118:119], v[54:55]
	v_pk_fma_f32 v[52:53], v[120:121], v[120:121], v[52:53]
	v_pk_fma_f32 v[54:55], v[122:123], v[122:123], v[54:55]
	v_pk_fma_f32 v[52:53], v[124:125], v[124:125], v[52:53]
	v_pk_fma_f32 v[54:55], v[126:127], v[126:127], v[54:55]
	v_pk_add_f32 v[52:53], v[52:53], v[54:55]
	v_add_f32_e32 v97, v52, v53
	s_nop 1
	v_add_f32_dpp v97, v97, v97 quad_perm:[1,0,3,2] row_mask:0xf bank_mask:0xf
	s_nop 1
	v_add_f32_dpp v97, v97, v97 quad_perm:[2,3,0,1] row_mask:0xf bank_mask:0xf
	s_nop 1
	v_add_f32_dpp v97, v97, v97 row_ror:4 row_mask:0xf bank_mask:0xf
	s_nop 1
	v_add_f32_dpp v97, v97, v97 row_ror:8 row_mask:0xf bank_mask:0xf
	ds_bpermute_b32 v103, v108, v97
	v_add_u32_e32 v58, 0x3000, v96
	v_mov_b32_e32 v59, v147
	v_lshlrev_b64 v[92:93], 11, v[58:59]
	v_lshl_add_u64 v[92:93], v[100:101], 0, v[92:93]
	s_waitcnt lgkmcnt(0)
	v_add_f32_e32 v103, v97, v103
	ds_bpermute_b32 v106, v109, v103
	s_waitcnt lgkmcnt(0)
; DI unsigned pk2(float lo, float hi) { const f32x2 v = {lo, hi}; const hbf16x2 b = __builtin_convertvector(v, hbf16x2); return __builtin_bit_cast(unsigned, b); }
; DI void norm_phase(const Ctx& a, int layer, int sub, bool first, const float* P, int nsl, int nrows) {
;     ...
; #pragma unroll
;         for (int j = 0; j < 4; ++j) ss += (v[j][0] * v[j][0] + v[j][1] * v[j][1]) + (v[j][2] * v[j][2] + v[j][3] * v[j][3]);
;         const float rstd = 1.f / sqrtf(wave_sum(ss, lane) * (1.f / 1024.f) + 1e-6f);
; #pragma unroll
;         for (int j = 0; j < 4; ++j) {
;             const int c = 4 * lane + 256 * j;
;             if ((first && row >= ML) || fold) *(f32x4*)(H + (size_t)row * 1024 + c) = v[j];
;             f32x4 y = v[j] * rstd * gg[j]; y = y * sc[j] + sh[j];
;             u32x2 w; w.x = pk2(y[0], y[1]); w.y = pk2(y[2], y[3]);
;             *(u32x2*)(XN + (size_t)row * 1024 + c) = w;
;         }
	v_add_f32_e32 v97, v103, v106
	v_fmamk_f32 v97, v97, 0x3a800000, v203
	v_mul_f32_e32 v103, 0x4f800000, v97
	v_cmp_gt_f32_e32 vcc, s26, v97
	s_nop 1
	v_cndmask_b32_e32 v97, v97, v103, vcc
	v_sqrt_f32_e32 v103, v97
	s_nop 0
	v_add_u32_e32 v106, -1, v103
	v_fma_f32 v111, -v106, v103, v97
	v_add_u32_e32 v107, 1, v103
	v_cmp_ge_f32_e64 s[42:43], 0, v111
	s_nop 1
	v_cndmask_b32_e64 v106, v103, v106, s[42:43]
	v_fma_f32 v103, -v107, v103, v97
	v_cmp_lt_f32_e64 s[42:43], 0, v103
	s_nop 1
	v_cndmask_b32_e64 v103, v106, v107, s[42:43]
	v_mul_f32_e32 v106, 0x37800000, v103
	v_cndmask_b32_e32 v103, v103, v106, vcc
	v_cmp_class_f32_e32 vcc, v97, v201
	s_nop 1
	v_cndmask_b32_e32 v97, v103, v97, vcc
	v_div_scale_f32 v103, s[30:31], v97, v97, 1.0
	v_rcp_f32_e32 v106, v103
	s_nop 0
	v_fma_f32 v107, -v103, v106, 1.0
	v_fmac_f32_e32 v106, v107, v106
	v_div_scale_f32 v107, vcc, 1.0, v97, 1.0
	v_mul_f32_e32 v111, v107, v106
	v_fma_f32 v45, -v103, v111, v107
	v_fmac_f32_e32 v111, v45, v106
	v_fma_f32 v103, -v103, v111, v107
	v_div_fmas_f32 v103, v103, v106, v111
	v_div_fixup_f32 v106, v103, v97, 1.0
	v_mov_b32_e32 v107, v106
	v_pk_mul_f32 v[112:113], v[112:113], v[106:107]
	v_pk_mul_f32 v[114:115], v[114:115], v[106:107]
	v_pk_mul_f32 v[112:113], v[0:1], v[112:113]
	v_pk_mul_f32 v[114:115], v[2:3], v[114:115]
	v_pk_fma_f32 v[112:113], v[174:175], v[112:113], v[158:159]
	v_pk_fma_f32 v[114:115], v[176:177], v[114:115], v[160:161]
	v_cvt_pk_bf16_f32 v54, v112, v113
	v_cvt_pk_bf16_f32 v55, v114, v115
	global_store_dwordx2 v[92:93], v[54:55], off
	v_pk_mul_f32 v[116:117], v[116:117], v[106:107]
	v_pk_mul_f32 v[118:119], v[118:119], v[106:107]
	v_pk_mul_f32 v[116:117], v[4:5], v[116:117]
	v_pk_mul_f32 v[118:119], v[6:7], v[118:119]
	v_pk_fma_f32 v[116:117], v[178:179], v[116:117], v[162:163]
	v_pk_fma_f32 v[118:119], v[180:181], v[118:119], v[164:165]
	v_cvt_pk_bf16_f32 v56, v116, v117
	v_cvt_pk_bf16_f32 v57, v118, v119
	global_store_dwordx2 v[92:93], v[56:57], off offset:512
	v_pk_mul_f32 v[120:121], v[120:121], v[106:107]
	v_pk_mul_f32 v[122:123], v[122:123], v[106:107]
	v_pk_mul_f32 v[120:121], v[8:9], v[120:121]
	v_pk_mul_f32 v[122:123], v[10:11], v[122:123]
	v_pk_fma_f32 v[120:121], v[182:183], v[120:121], v[166:167]
	v_pk_fma_f32 v[122:123], v[184:185], v[122:123], v[168:169]
	v_cvt_pk_bf16_f32 v54, v120, v121
	v_cvt_pk_bf16_f32 v55, v122, v123
	global_store_dwordx2 v[92:93], v[54:55], off offset:1024
	v_pk_mul_f32 v[124:125], v[124:125], v[106:107]
	v_pk_mul_f32 v[126:127], v[126:127], v[106:107]
	v_pk_mul_f32 v[124:125], v[12:13], v[124:125]
	v_pk_mul_f32 v[126:127], v[14:15], v[126:127]
	v_pk_fma_f32 v[124:125], v[186:187], v[124:125], v[170:171]
	v_pk_fma_f32 v[126:127], v[188:189], v[126:127], v[172:173]
	v_cvt_pk_bf16_f32 v56, v124, v125
	v_cvt_pk_bf16_f32 v57, v126, v127
	global_store_dwordx2 v[92:93], v[56:57], off offset:1536
	v_pk_mul_f32 v[52:53], v[128:129], v[128:129]
	v_pk_mul_f32 v[54:55], v[130:131], v[130:131]
	v_pk_fma_f32 v[52:53], v[132:133], v[132:133], v[52:53]
	v_pk_fma_f32 v[54:55], v[134:135], v[134:135], v[54:55]
	v_pk_fma_f32 v[52:53], v[136:137], v[136:137], v[52:53]
	v_pk_fma_f32 v[54:55], v[138:139], v[138:139], v[54:55]
	v_pk_fma_f32 v[52:53], v[140:141], v[140:141], v[52:53]
	v_pk_fma_f32 v[54:55], v[142:143], v[142:143], v[54:55]
	v_pk_add_f32 v[52:53], v[52:53], v[54:55]
	v_add_f32_e32 v97, v52, v53
	s_nop 1
	v_add_f32_dpp v97, v97, v97 quad_perm:[1,0,3,2] row_mask:0xf bank_mask:0xf
	s_nop 1
	v_add_f32_dpp v97, v97, v97 quad_perm:[2,3,0,1] row_mask:0xf bank_mask:0xf
	s_nop 1
	v_add_f32_dpp v97, v97, v97 row_ror:4 row_mask:0xf bank_mask:0xf
	s_nop 1
	v_add_f32_dpp v97, v97, v97 row_ror:8 row_mask:0xf bank_mask:0xf
	ds_bpermute_b32 v103, v108, v97
	v_add_u32_e32 v58, 0x3800, v96
	v_mov_b32_e32 v59, v147
	v_lshlrev_b64 v[92:93], 11, v[58:59]
	v_lshl_add_u64 v[92:93], v[100:101], 0, v[92:93]
	s_waitcnt lgkmcnt(0)
	v_add_f32_e32 v103, v97, v103
	ds_bpermute_b32 v106, v109, v103
	s_waitcnt lgkmcnt(0)
	v_add_f32_e32 v97, v103, v106
	v_fmamk_f32 v97, v97, 0x3a800000, v203
	v_mul_f32_e32 v103, 0x4f800000, v97
	v_cmp_gt_f32_e32 vcc, s26, v97
	s_nop 1
	v_cndmask_b32_e32 v97, v97, v103, vcc
	v_sqrt_f32_e32 v103, v97
	s_nop 0
	v_add_u32_e32 v106, -1, v103
	v_fma_f32 v111, -v106, v103, v97
	v_add_u32_e32 v107, 1, v103
	v_cmp_ge_f32_e64 s[42:43], 0, v111
	s_nop 1
	v_cndmask_b32_e64 v106, v103, v106, s[42:43]
	v_fma_f32 v103, -v107, v103, v97
	v_cmp_lt_f32_e64 s[42:43], 0, v103
	s_nop 1
	v_cndmask_b32_e64 v103, v106, v107, s[42:43]
	v_mul_f32_e32 v106, 0x37800000, v103
	v_cndmask_b32_e32 v103, v103, v106, vcc
	v_cmp_class_f32_e32 vcc, v97, v201
	s_nop 1
	v_cndmask_b32_e32 v97, v103, v97, vcc
	v_div_scale_f32 v103, s[30:31], v97, v97, 1.0
	v_rcp_f32_e32 v106, v103
	s_nop 0
	v_fma_f32 v107, -v103, v106, 1.0
	v_fmac_f32_e32 v106, v107, v106
	v_div_scale_f32 v107, vcc, 1.0, v97, 1.0
	v_mul_f32_e32 v111, v107, v106
	v_fma_f32 v45, -v103, v111, v107
	v_fmac_f32_e32 v111, v45, v106
	v_fma_f32 v103, -v103, v111, v107
	v_div_fmas_f32 v103, v103, v106, v111
	v_div_fixup_f32 v106, v103, v97, 1.0
	v_mov_b32_e32 v107, v106
	v_pk_mul_f32 v[128:129], v[128:129], v[106:107]
	v_pk_mul_f32 v[130:131], v[130:131], v[106:107]
	v_pk_mul_f32 v[128:129], v[0:1], v[128:129]
	v_pk_mul_f32 v[130:131], v[2:3], v[130:131]
	v_pk_fma_f32 v[128:129], v[174:175], v[128:129], v[158:159]
	v_pk_fma_f32 v[130:131], v[176:177], v[130:131], v[160:161]
	v_cvt_pk_bf16_f32 v54, v128, v129
	v_cvt_pk_bf16_f32 v55, v130, v131
	global_store_dwordx2 v[92:93], v[54:55], off
	v_pk_mul_f32 v[132:133], v[132:133], v[106:107]
	v_pk_mul_f32 v[134:135], v[134:135], v[106:107]
	v_pk_mul_f32 v[132:133], v[4:5], v[132:133]
	v_pk_mul_f32 v[134:135], v[6:7], v[134:135]
	v_pk_fma_f32 v[132:133], v[178:179], v[132:133], v[162:163]
	v_pk_fma_f32 v[134:135], v[180:181], v[134:135], v[164:165]
	v_cvt_pk_bf16_f32 v56, v132, v133
	v_cvt_pk_bf16_f32 v57, v134, v135
	global_store_dwordx2 v[92:93], v[56:57], off offset:512
	v_pk_mul_f32 v[136:137], v[136:137], v[106:107]
	v_pk_mul_f32 v[138:139], v[138:139], v[106:107]
	v_pk_mul_f32 v[136:137], v[8:9], v[136:137]
	v_pk_mul_f32 v[138:139], v[10:11], v[138:139]
	v_pk_fma_f32 v[136:137], v[182:183], v[136:137], v[166:167]
	v_pk_fma_f32 v[138:139], v[184:185], v[138:139], v[168:169]
	v_cvt_pk_bf16_f32 v54, v136, v137
	v_cvt_pk_bf16_f32 v55, v138, v139
	global_store_dwordx2 v[92:93], v[54:55], off offset:1024
	v_pk_mul_f32 v[140:141], v[140:141], v[106:107]
	v_pk_mul_f32 v[142:143], v[142:143], v[106:107]
	v_pk_mul_f32 v[140:141], v[12:13], v[140:141]
	v_pk_mul_f32 v[142:143], v[14:15], v[142:143]
	v_pk_fma_f32 v[140:141], v[186:187], v[140:141], v[170:171]
	v_pk_fma_f32 v[142:143], v[188:189], v[142:143], v[172:173]
	v_cvt_pk_bf16_f32 v56, v140, v141
	v_cvt_pk_bf16_f32 v57, v142, v143
	global_store_dwordx2 v[92:93], v[56:57], off offset:1536
	v_add_u32_e32 v96, 0x4000, v96
	v_cmp_gt_i32_e32 vcc, s37, v96
	s_cbranch_vccz .Lnp_fast_done
; DI void norm_phase(const Ctx& a, int layer, int sub, bool first, const float* P, int nsl, int nrows) {
;     ...
;         const int mr = row < ML ? (row >> 12) : 4;
;         if (mr != mr_cur) { mr_cur = mr;
; #pragma unroll
;             for (int j = 0; j < 4; ++j) { sh[j] = *(const f32x4*)(modl + (size_t)mr * MODW + 4 * lane + 256 * j); sc[j] = *(const f32x4*)(modl + (size_t)mr * MODW + 1024 + 4 * lane + 256 * j) + 1.f; } }
;         const bool fold = !first && row >= ML;
;         float ss = 0.f;
;         if (fold) {
;             for (int sl0 = 0; sl0 < nsl; sl0 += 4) {
;                 f32x4 t[4][4]; float wq[4];
; #pragma unroll
;                 for (int u = 0; u < 4; ++u) { const int sl = sl0 + u < nsl ? sl0 + u : nsl - 1; wq[u] = sl0 + u < nsl ? 1.f : 0.f;
; #pragma unroll
;                     for (int j = 0; j < 4; ++j) t[u][j] = *(const f32x4*)(P + ((size_t)sl * MC + (row - ML)) * D + 4 * lane + 256 * j); }
; #pragma unroll
;                 for (int u = 0; u < 4; ++u)
; #pragma unroll
;                     for (int j = 0; j < 4; ++j) v[j] = v[j] + t[u][j] * wq[u];
;             }
;         }
	v_mov_b32_e32 v97, v147
	v_lshlrev_b64 v[94:95], 12, v[96:97]
	v_lshl_add_u64 v[94:95], s[34:35], 0, v[94:95]
	v_lshl_add_u64 v[44:45], v[94:95], 0, v[146:147]
	global_load_dwordx4 v[28:31], v[44:45], off
	global_load_dwordx4 v[24:27], v[44:45], off offset:1024
	global_load_dwordx4 v[20:23], v[44:45], off offset:2048
	global_load_dwordx4 v[16:19], v[44:45], off offset:3072
	s_add_u32 s20, s38, 0x24000
	s_addc_u32 s21, s39, 0
	v_lshl_add_u64 v[94:95], s[20:21], 0, v[146:147]
	global_load_dwordx4 v[60:63], v[94:95], off
	global_load_dwordx4 v[64:67], v[94:95], off offset:1024
	global_load_dwordx4 v[68:71], v[94:95], off offset:2048
	global_load_dwordx4 v[72:75], v[94:95], off offset:3072
	s_add_u32 s20, s20, 0x1000
	s_addc_u32 s21, s21, 0
	v_lshl_add_u64 v[94:95], s[20:21], 0, v[146:147]
	global_load_dwordx4 v[76:79], v[94:95], off
	global_load_dwordx4 v[80:83], v[94:95], off offset:1024
	global_load_dwordx4 v[84:87], v[94:95], off offset:2048
	global_load_dwordx4 v[88:91], v[94:95], off offset:3072
	v_add_u32_e32 v58, 0xffffc000, v96
	v_mov_b32_e32 v59, v147
	v_lshlrev_b64 v[58:59], 12, v[58:59]
	v_lshl_add_u64 v[58:59], v[98:99], 0, v[58:59]
	s_min_u32 s20, 0, s49
	s_mov_b32 s21, 0
	s_lshl_b64 s[20:21], s[20:21], 22
	v_lshl_add_u64 v[94:95], v[58:59], 0, s[20:21]
	global_load_dwordx4 v[36:39], v[94:95], off
	global_load_dwordx4 v[40:43], v[94:95], off offset:1024
	global_load_dwordx4 v[48:51], v[94:95], off offset:2048
	global_load_dwordx4 v[32:35], v[94:95], off offset:3072
	s_min_u32 s20, 1, s49
	s_mov_b32 s21, 0
	s_lshl_b64 s[20:21], s[20:21], 22
	v_lshl_add_u64 v[94:95], v[58:59], 0, s[20:21]
	global_load_dwordx4 v[112:115], v[94:95], off
	global_load_dwordx4 v[116:119], v[94:95], off offset:1024
	global_load_dwordx4 v[120:123], v[94:95], off offset:2048
	global_load_dwordx4 v[124:127], v[94:95], off offset:3072
	s_min_u32 s20, 2, s49
	s_mov_b32 s21, 0
	s_lshl_b64 s[20:21], s[20:21], 22
	v_lshl_add_u64 v[94:95], v[58:59], 0, s[20:21]
	global_load_dwordx4 v[128:131], v[94:95], off
	global_load_dwordx4 v[132:135], v[94:95], off offset:1024
	global_load_dwordx4 v[136:139], v[94:95], off offset:2048
	global_load_dwordx4 v[140:143], v[94:95], off offset:3072
	s_min_u32 s20, 3, s49
	s_mov_b32 s21, 0
	s_lshl_b64 s[20:21], s[20:21], 22
	v_lshl_add_u64 v[94:95], v[58:59], 0, s[20:21]
	global_load_dwordx4 v[158:161], v[94:95], off
	global_load_dwordx4 v[162:165], v[94:95], off offset:1024
	global_load_dwordx4 v[166:169], v[94:95], off offset:2048
	global_load_dwordx4 v[170:173], v[94:95], off offset:3072
	s_min_u32 s20, 4, s49
	s_mov_b32 s21, 0
	s_lshl_b64 s[20:21], s[20:21], 22
	v_lshl_add_u64 v[94:95], v[58:59], 0, s[20:21]
	global_load_dwordx4 v[174:177], v[94:95], off
	global_load_dwordx4 v[178:181], v[94:95], off offset:1024
	global_load_dwordx4 v[182:185], v[94:95], off offset:2048
	global_load_dwordx4 v[186:189], v[94:95], off offset:3072
	s_min_u32 s20, 5, s49
	s_mov_b32 s21, 0
	s_lshl_b64 s[20:21], s[20:21], 22
	v_lshl_add_u64 v[94:95], v[58:59], 0, s[20:21]
	global_load_dwordx4 v[190:193], v[94:95], off
	global_load_dwordx4 v[194:197], v[94:95], off offset:1024
	global_load_dwordx4 v[206:209], v[94:95], off offset:2048
	global_load_dwordx4 v[220:223], v[94:95], off offset:3072
	s_min_u32 s20, 6, s49
	s_mov_b32 s21, 0
	s_lshl_b64 s[20:21], s[20:21], 22
	v_lshl_add_u64 v[94:95], v[58:59], 0, s[20:21]
	global_load_dwordx4 v[230:233], v[94:95], off
	global_load_dwordx4 v[234:237], v[94:95], off offset:1024
	global_load_dwordx4 v[238:241], v[94:95], off offset:2048
	global_load_dwordx4 v[242:245], v[94:95], off offset:3072
	s_waitcnt vmcnt(36)
	s_waitcnt vmcnt(24)
	s_cmp_lt_u32 0, s48
	s_cbranch_scc0 .Lnp_cx_skip0
	v_pk_add_f32 v[28:29], v[28:29], v[36:37]
	v_pk_add_f32 v[30:31], v[30:31], v[38:39]
	v_pk_add_f32 v[24:25], v[24:25], v[40:41]
	v_pk_add_f32 v[26:27], v[26:27], v[42:43]
	v_pk_add_f32 v[20:21], v[20:21], v[48:49]
	v_pk_add_f32 v[22:23], v[22:23], v[50:51]
	v_pk_add_f32 v[16:17], v[16:17], v[32:33]
	v_pk_add_f32 v[18:19], v[18:19], v[34:35]
.Lnp_cx_skip0:
	s_min_u32 s20, 7, s49
	s_mov_b32 s21, 0
	s_lshl_b64 s[20:21], s[20:21], 22
	v_lshl_add_u64 v[94:95], v[58:59], 0, s[20:21]
	global_load_dwordx4 v[36:39], v[94:95], off
	global_load_dwordx4 v[40:43], v[94:95], off offset:1024
	global_load_dwordx4 v[48:51], v[94:95], off offset:2048
	global_load_dwordx4 v[32:35], v[94:95], off offset:3072
	s_waitcnt vmcnt(24)
	s_cmp_lt_u32 1, s48
	s_cbranch_scc0 .Lnp_cx_skip1
	v_pk_add_f32 v[28:29], v[28:29], v[112:113]
	v_pk_add_f32 v[30:31], v[30:31], v[114:115]
	v_pk_add_f32 v[24:25], v[24:25], v[116:117]
	v_pk_add_f32 v[26:27], v[26:27], v[118:119]
	v_pk_add_f32 v[20:21], v[20:21], v[120:121]
	v_pk_add_f32 v[22:23], v[22:23], v[122:123]
	v_pk_add_f32 v[16:17], v[16:17], v[124:125]
	v_pk_add_f32 v[18:19], v[18:19], v[126:127]
.Lnp_cx_skip1:
	s_min_u32 s20, 8, s49
	s_mov_b32 s21, 0
	s_lshl_b64 s[20:21], s[20:21], 22
	v_lshl_add_u64 v[94:95], v[58:59], 0, s[20:21]
	global_load_dwordx4 v[112:115], v[94:95], off
	global_load_dwordx4 v[116:119], v[94:95], off offset:1024
	global_load_dwordx4 v[120:123], v[94:95], off offset:2048
	global_load_dwordx4 v[124:127], v[94:95], off offset:3072
	s_waitcnt vmcnt(24)
	s_cmp_lt_u32 2, s48
	s_cbranch_scc0 .Lnp_cx_skip2
	v_pk_add_f32 v[28:29], v[28:29], v[128:129]
	v_pk_add_f32 v[30:31], v[30:31], v[130:131]
	v_pk_add_f32 v[24:25], v[24:25], v[132:133]
	v_pk_add_f32 v[26:27], v[26:27], v[134:135]
	v_pk_add_f32 v[20:21], v[20:21], v[136:137]
	v_pk_add_f32 v[22:23], v[22:23], v[138:139]
	v_pk_add_f32 v[16:17], v[16:17], v[140:141]
	v_pk_add_f32 v[18:19], v[18:19], v[142:143]
; DI void norm_phase(const Ctx& a, int layer, int sub, bool first, const float* P, int nsl, int nrows) {
;     ...
;         if (fold) {
;             for (int sl0 = 0; sl0 < nsl; sl0 += 4) {
;                 f32x4 t[4][4]; float wq[4];
; #pragma unroll
;                 for (int u = 0; u < 4; ++u) { const int sl = sl0 + u < nsl ? sl0 + u : nsl - 1; wq[u] = sl0 + u < nsl ? 1.f : 0.f;
; #pragma unroll
;                     for (int j = 0; j < 4; ++j) t[u][j] = *(const f32x4*)(P + ((size_t)sl * MC + (row - ML)) * D + 4 * lane + 256 * j); }
; #pragma unroll
;                 for (int u = 0; u < 4; ++u)
; #pragma unroll
;                     for (int j = 0; j < 4; ++j) v[j] = v[j] + t[u][j] * wq[u];
;             }
;         }
.Lnp_cx_skip2:
	s_min_u32 s20, 9, s49
	s_mov_b32 s21, 0
	s_lshl_b64 s[20:21], s[20:21], 22
	v_lshl_add_u64 v[94:95], v[58:59], 0, s[20:21]
	global_load_dwordx4 v[128:131], v[94:95], off
	global_load_dwordx4 v[132:135], v[94:95], off offset:1024
	global_load_dwordx4 v[136:139], v[94:95], off offset:2048
	global_load_dwordx4 v[140:143], v[94:95], off offset:3072
	s_waitcnt vmcnt(24)
	s_cmp_lt_u32 3, s48
	s_cbranch_scc0 .Lnp_cx_skip3
	v_pk_add_f32 v[28:29], v[28:29], v[158:159]
	v_pk_add_f32 v[30:31], v[30:31], v[160:161]
	v_pk_add_f32 v[24:25], v[24:25], v[162:163]
	v_pk_add_f32 v[26:27], v[26:27], v[164:165]
	v_pk_add_f32 v[20:21], v[20:21], v[166:167]
	v_pk_add_f32 v[22:23], v[22:23], v[168:169]
	v_pk_add_f32 v[16:17], v[16:17], v[170:171]
	v_pk_add_f32 v[18:19], v[18:19], v[172:173]
.Lnp_cx_skip3:
	s_min_u32 s20, 10, s49
	s_mov_b32 s21, 0
	s_lshl_b64 s[20:21], s[20:21], 22
	v_lshl_add_u64 v[94:95], v[58:59], 0, s[20:21]
	global_load_dwordx4 v[158:161], v[94:95], off
	global_load_dwordx4 v[162:165], v[94:95], off offset:1024
	global_load_dwordx4 v[166:169], v[94:95], off offset:2048
	global_load_dwordx4 v[170:173], v[94:95], off offset:3072
	s_waitcnt vmcnt(24)
	s_cmp_lt_u32 4, s48
	s_cbranch_scc0 .Lnp_cx_skip4
	v_pk_add_f32 v[28:29], v[28:29], v[174:175]
	v_pk_add_f32 v[30:31], v[30:31], v[176:177]
	v_pk_add_f32 v[24:25], v[24:25], v[178:179]
	v_pk_add_f32 v[26:27], v[26:27], v[180:181]
	v_pk_add_f32 v[20:21], v[20:21], v[182:183]
	v_pk_add_f32 v[22:23], v[22:23], v[184:185]
	v_pk_add_f32 v[16:17], v[16:17], v[186:187]
	v_pk_add_f32 v[18:19], v[18:19], v[188:189]
.Lnp_cx_skip4:
	s_waitcnt vmcnt(20)
	s_cmp_lt_u32 5, s48
	s_cbranch_scc0 .Lnp_cx_skip5
	v_pk_add_f32 v[28:29], v[28:29], v[190:191]
	v_pk_add_f32 v[30:31], v[30:31], v[192:193]
	v_pk_add_f32 v[24:25], v[24:25], v[194:195]
	v_pk_add_f32 v[26:27], v[26:27], v[196:197]
	v_pk_add_f32 v[20:21], v[20:21], v[206:207]
	v_pk_add_f32 v[22:23], v[22:23], v[208:209]
	v_pk_add_f32 v[16:17], v[16:17], v[220:221]
	v_pk_add_f32 v[18:19], v[18:19], v[222:223]
.Lnp_cx_skip5:
	s_waitcnt vmcnt(16)
	s_cmp_lt_u32 6, s48
	s_cbranch_scc0 .Lnp_cx_skip6
	v_pk_add_f32 v[28:29], v[28:29], v[230:231]
	v_pk_add_f32 v[30:31], v[30:31], v[232:233]
	v_pk_add_f32 v[24:25], v[24:25], v[234:235]
	v_pk_add_f32 v[26:27], v[26:27], v[236:237]
	v_pk_add_f32 v[20:21], v[20:21], v[238:239]
	v_pk_add_f32 v[22:23], v[22:23], v[240:241]
	v_pk_add_f32 v[16:17], v[16:17], v[242:243]
	v_pk_add_f32 v[18:19], v[18:19], v[244:245]
.Lnp_cx_skip6:
	s_waitcnt vmcnt(12)
	s_cmp_lt_u32 7, s48
	s_cbranch_scc0 .Lnp_cx_skip7
	v_pk_add_f32 v[28:29], v[28:29], v[36:37]
	v_pk_add_f32 v[30:31], v[30:31], v[38:39]
	v_pk_add_f32 v[24:25], v[24:25], v[40:41]
	v_pk_add_f32 v[26:27], v[26:27], v[42:43]
	v_pk_add_f32 v[20:21], v[20:21], v[48:49]
	v_pk_add_f32 v[22:23], v[22:23], v[50:51]
	v_pk_add_f32 v[16:17], v[16:17], v[32:33]
	v_pk_add_f32 v[18:19], v[18:19], v[34:35]
.Lnp_cx_skip7:
	s_waitcnt vmcnt(8)
	s_cmp_lt_u32 8, s48
	s_cbranch_scc0 .Lnp_cx_skip8
	v_pk_add_f32 v[28:29], v[28:29], v[112:113]
	v_pk_add_f32 v[30:31], v[30:31], v[114:115]
	v_pk_add_f32 v[24:25], v[24:25], v[116:117]
	v_pk_add_f32 v[26:27], v[26:27], v[118:119]
	v_pk_add_f32 v[20:21], v[20:21], v[120:121]
	v_pk_add_f32 v[22:23], v[22:23], v[122:123]
	v_pk_add_f32 v[16:17], v[16:17], v[124:125]
	v_pk_add_f32 v[18:19], v[18:19], v[126:127]
.Lnp_cx_skip8:
	s_waitcnt vmcnt(4)
	s_cmp_lt_u32 9, s48
	s_cbranch_scc0 .Lnp_cx_skip9
	v_pk_add_f32 v[28:29], v[28:29], v[128:129]
	v_pk_add_f32 v[30:31], v[30:31], v[130:131]
	v_pk_add_f32 v[24:25], v[24:25], v[132:133]
	v_pk_add_f32 v[26:27], v[26:27], v[134:135]
	v_pk_add_f32 v[20:21], v[20:21], v[136:137]
	v_pk_add_f32 v[22:23], v[22:23], v[138:139]
	v_pk_add_f32 v[16:17], v[16:17], v[140:141]
	v_pk_add_f32 v[18:19], v[18:19], v[142:143]
.Lnp_cx_skip9:
	s_waitcnt vmcnt(0)
	s_cmp_lt_u32 10, s48
	s_cbranch_scc0 .Lnp_cx_skip10
	v_pk_add_f32 v[28:29], v[28:29], v[158:159]
	v_pk_add_f32 v[30:31], v[30:31], v[160:161]
	v_pk_add_f32 v[24:25], v[24:25], v[162:163]
	v_pk_add_f32 v[26:27], v[26:27], v[164:165]
	v_pk_add_f32 v[20:21], v[20:21], v[166:167]
	v_pk_add_f32 v[22:23], v[22:23], v[168:169]
	v_pk_add_f32 v[16:17], v[16:17], v[170:171]
	v_pk_add_f32 v[18:19], v[18:19], v[172:173]
; DI unsigned pk2(float lo, float hi) { const f32x2 v = {lo, hi}; const hbf16x2 b = __builtin_convertvector(v, hbf16x2); return __builtin_bit_cast(unsigned, b); }
; DI void norm_phase(const Ctx& a, int layer, int sub, bool first, const float* P, int nsl, int nrows) {
;     ...
; #pragma unroll
;         for (int j = 0; j < 4; ++j) ss += (v[j][0] * v[j][0] + v[j][1] * v[j][1]) + (v[j][2] * v[j][2] + v[j][3] * v[j][3]);
;         const float rstd = 1.f / sqrtf(wave_sum(ss, lane) * (1.f / 1024.f) + 1e-6f);
; #pragma unroll
;         for (int j = 0; j < 4; ++j) {
;             const int c = 4 * lane + 256 * j;
;             if ((first && row >= ML) || fold) *(f32x4*)(H + (size_t)row * 1024 + c) = v[j];
;             f32x4 y = v[j] * rstd * gg[j]; y = y * sc[j] + sh[j];
;             u32x2 w; w.x = pk2(y[0], y[1]); w.y = pk2(y[2], y[3]);
;             *(u32x2*)(XN + (size_t)row * 1024 + c) = w;
;         }
.Lnp_cx_skip10:
	global_store_dwordx4 v[44:45], v[28:31], off
	global_store_dwordx4 v[44:45], v[24:27], off offset:1024
	global_store_dwordx4 v[44:45], v[20:23], off offset:2048
	global_store_dwordx4 v[44:45], v[16:19], off offset:3072
	v_pk_add_f32 v[76:77], v[76:77], 1.0 op_sel_hi:[1,0]
	v_pk_add_f32 v[78:79], v[78:79], 1.0 op_sel_hi:[1,0]
	v_pk_add_f32 v[80:81], v[80:81], 1.0 op_sel_hi:[1,0]
	v_pk_add_f32 v[82:83], v[82:83], 1.0 op_sel_hi:[1,0]
	v_pk_add_f32 v[84:85], v[84:85], 1.0 op_sel_hi:[1,0]
	v_pk_add_f32 v[86:87], v[86:87], 1.0 op_sel_hi:[1,0]
	v_pk_add_f32 v[88:89], v[88:89], 1.0 op_sel_hi:[1,0]
	v_pk_add_f32 v[90:91], v[90:91], 1.0 op_sel_hi:[1,0]
	v_pk_mul_f32 v[52:53], v[28:29], v[28:29]
	v_pk_mul_f32 v[54:55], v[30:31], v[30:31]
	v_pk_fma_f32 v[52:53], v[24:25], v[24:25], v[52:53]
	v_pk_fma_f32 v[54:55], v[26:27], v[26:27], v[54:55]
	v_pk_fma_f32 v[52:53], v[20:21], v[20:21], v[52:53]
	v_pk_fma_f32 v[54:55], v[22:23], v[22:23], v[54:55]
	v_pk_fma_f32 v[52:53], v[16:17], v[16:17], v[52:53]
	v_pk_fma_f32 v[54:55], v[18:19], v[18:19], v[54:55]
	v_pk_add_f32 v[52:53], v[52:53], v[54:55]
	v_add_f32_e32 v97, v52, v53
	s_nop 1
	v_add_f32_dpp v97, v97, v97 quad_perm:[1,0,3,2] row_mask:0xf bank_mask:0xf
	s_nop 1
	v_add_f32_dpp v97, v97, v97 quad_perm:[2,3,0,1] row_mask:0xf bank_mask:0xf
	s_nop 1
	v_add_f32_dpp v97, v97, v97 row_ror:4 row_mask:0xf bank_mask:0xf
	s_nop 1
	v_add_f32_dpp v97, v97, v97 row_ror:8 row_mask:0xf bank_mask:0xf
	ds_bpermute_b32 v103, v108, v97
	v_add_u32_e32 v58, 0x0, v96
	v_mov_b32_e32 v59, v147
	v_lshlrev_b64 v[92:93], 11, v[58:59]
	v_lshl_add_u64 v[92:93], v[100:101], 0, v[92:93]
	s_waitcnt lgkmcnt(0)
	v_add_f32_e32 v103, v97, v103
	ds_bpermute_b32 v106, v109, v103
	s_waitcnt lgkmcnt(0)
	v_add_f32_e32 v97, v103, v106
	v_fmamk_f32 v97, v97, 0x3a800000, v203
	v_mul_f32_e32 v103, 0x4f800000, v97
	v_cmp_gt_f32_e32 vcc, s26, v97
	s_nop 1
	v_cndmask_b32_e32 v97, v97, v103, vcc
	v_sqrt_f32_e32 v103, v97
	s_nop 0
	v_add_u32_e32 v106, -1, v103
	v_fma_f32 v111, -v106, v103, v97
	v_add_u32_e32 v107, 1, v103
	v_cmp_ge_f32_e64 s[42:43], 0, v111
	s_nop 1
	v_cndmask_b32_e64 v106, v103, v106, s[42:43]
	v_fma_f32 v103, -v107, v103, v97
	v_cmp_lt_f32_e64 s[42:43], 0, v103
	s_nop 1
	v_cndmask_b32_e64 v103, v106, v107, s[42:43]
	v_mul_f32_e32 v106, 0x37800000, v103
	v_cndmask_b32_e32 v103, v103, v106, vcc
	v_cmp_class_f32_e32 vcc, v97, v201
	s_nop 1
	v_cndmask_b32_e32 v97, v103, v97, vcc
	v_div_scale_f32 v103, s[30:31], v97, v97, 1.0
	v_rcp_f32_e32 v106, v103
	s_nop 0
	v_fma_f32 v107, -v103, v106, 1.0
	v_fmac_f32_e32 v106, v107, v106
	v_div_scale_f32 v107, vcc, 1.0, v97, 1.0
	v_mul_f32_e32 v111, v107, v106
	v_fma_f32 v45, -v103, v111, v107
	v_fmac_f32_e32 v111, v45, v106
	v_fma_f32 v103, -v103, v111, v107
	v_div_fmas_f32 v103, v103, v106, v111
	v_div_fixup_f32 v106, v103, v97, 1.0
	v_mov_b32_e32 v107, v106
	v_pk_mul_f32 v[28:29], v[28:29], v[106:107]
	v_pk_mul_f32 v[30:31], v[30:31], v[106:107]
	v_pk_mul_f32 v[28:29], v[0:1], v[28:29]
	v_pk_mul_f32 v[30:31], v[2:3], v[30:31]
	v_pk_fma_f32 v[28:29], v[76:77], v[28:29], v[60:61]
	v_pk_fma_f32 v[30:31], v[78:79], v[30:31], v[62:63]
	v_cvt_pk_bf16_f32 v54, v28, v29
	v_cvt_pk_bf16_f32 v55, v30, v31
	global_store_dwordx2 v[92:93], v[54:55], off
	v_pk_mul_f32 v[24:25], v[24:25], v[106:107]
	v_pk_mul_f32 v[26:27], v[26:27], v[106:107]
	v_pk_mul_f32 v[24:25], v[4:5], v[24:25]
	v_pk_mul_f32 v[26:27], v[6:7], v[26:27]
	v_pk_fma_f32 v[24:25], v[80:81], v[24:25], v[64:65]
	v_pk_fma_f32 v[26:27], v[82:83], v[26:27], v[66:67]
	v_cvt_pk_bf16_f32 v56, v24, v25
	v_cvt_pk_bf16_f32 v57, v26, v27
	global_store_dwordx2 v[92:93], v[56:57], off offset:512
	v_pk_mul_f32 v[20:21], v[20:21], v[106:107]
	v_pk_mul_f32 v[22:23], v[22:23], v[106:107]
	v_pk_mul_f32 v[20:21], v[8:9], v[20:21]
	v_pk_mul_f32 v[22:23], v[10:11], v[22:23]
	v_pk_fma_f32 v[20:21], v[84:85], v[20:21], v[68:69]
	v_pk_fma_f32 v[22:23], v[86:87], v[22:23], v[70:71]
	v_cvt_pk_bf16_f32 v54, v20, v21
	v_cvt_pk_bf16_f32 v55, v22, v23
	global_store_dwordx2 v[92:93], v[54:55], off offset:1024
	v_pk_mul_f32 v[16:17], v[16:17], v[106:107]
	v_pk_mul_f32 v[18:19], v[18:19], v[106:107]
	v_pk_mul_f32 v[16:17], v[12:13], v[16:17]
	v_pk_mul_f32 v[18:19], v[14:15], v[18:19]
	v_pk_fma_f32 v[16:17], v[88:89], v[16:17], v[72:73]
	v_pk_fma_f32 v[18:19], v[90:91], v[18:19], v[74:75]
	v_cvt_pk_bf16_f32 v56, v16, v17
	v_cvt_pk_bf16_f32 v57, v18, v19
	global_store_dwordx2 v[92:93], v[56:57], off offset:1536
